# GEMM2/GEMM4: trailing half's re-offset barrier moved after the unit header + zeroing (duplicated header on the post-epilogue path)
# baseline (speedup 1.0000x reference)
;     __device__ __forceinline__ bool next(int i, Unit& u) const { const int r = i / 9, tile = t0 + r * ts; if (r >= nr || tile >= 512) return false; u.pm = tile >> 2; u.pn = tile & 3; u.kind = i % 9; return true; }
;     __host__ __device__ bool next(int i, Unit& u) const {
;         const long L = (long)i * G + c; if (L >= nwg) return false;
;         int wgid = (int)L; { const int q = nwg / NXCD, r = nwg % NXCD, xcd = wgid % NXCD, off = wgid / NXCD; wgid = (xcd < r ? xcd * (q + 1) : r * (q + 1) + (xcd - r) * q) + off; }
;         const int nig = WGM * nN, gid = wgid / nig, fm = gid * WGM, gsz = (nM - fm) < WGM ? (nM - fm) : WGM;
;         u.pm = fm + ((wgid % nig) % gsz); u.pn = (wgid % nig) / gsz; u.kind = 1; return true;
; template <class Epi, class Sched, bool ALIGN_EPI = false, bool SP2 = false>
; __device__ __forceinline__ void gemm_phase(PG8_LAS unsigned char* lds, const Gemm g, const Sched& S, const Epi& E) {
;     ...
;         cur = nxt; cA = nA; cB = nB; ++ui;
.LBB0_192:
	s_andn2_b64 vcc, exec, s[18:19]
	s_mov_b32 s75, s48
	s_mov_b32 s42, s50
	s_mov_b64 s[58:59], s[54:55]
	s_mov_b64 s[56:57], s[52:53]
	s_cbranch_vccz .LBB0_218
	s_add_i32 s74, s74, 1
	s_mul_i32 s10, s74, s33
	s_mul_hi_u32 s11, s74, s86
	s_add_i32 s11, s11, s10
	s_mul_i32 s10, s74, s86
	s_add_u32 s52, s10, s97
	s_addc_u32 s53, s11, s8
	v_mov_b64_e32 v[0:1], 0x800
	v_cmp_lt_i64_e64 s[40:41], s[52:53], v[0:1]
	v_mov_b64_e32 v[0:1], 0x7ff
	v_cmp_gt_i64_e32 vcc, s[52:53], v[0:1]
	s_cbranch_vccnz .Lt2_199
	s_ashr_i32 s10, s52, 31
	s_lshr_b32 s10, s10, 29
	s_add_i32 s18, s52, s10
	s_and_b32 s10, s18, -8
	s_sub_i32 s19, s52, s10
	s_cmp_gt_i32 s19, -1
	s_mov_b64 s[48:49], -1
	s_cbranch_scc0 .Lt2_196
	s_lshl_b32 s20, s19, 8
	s_mov_b64 s[48:49], 0

; #define PG8_BAR __builtin_amdgcn_s_barrier()
;     __device__ __forceinline__ bool next(int i, Unit& u) const { const int r = i / 9, tile = t0 + r * ts; if (r >= nr || tile >= 512) return false; u.pm = tile >> 2; u.pn = tile & 3; u.kind = i % 9; return true; }
;     __host__ __device__ bool next(int i, Unit& u) const {
;         const long L = (long)i * G + c; if (L >= nwg) return false;
;         int wgid = (int)L; { const int q = nwg / NXCD, r = nwg % NXCD, xcd = wgid % NXCD, off = wgid / NXCD; wgid = (xcd < r ? xcd * (q + 1) : r * (q + 1) + (xcd - r) * q) + off; }
;         const int nig = WGM * nN, gid = wgid / nig, fm = gid * WGM, gsz = (nM - fm) < WGM ? (nM - fm) : WGM;
;         u.pm = fm + ((wgid % nig) % gsz); u.pn = (wgid % nig) / gsz; u.kind = 1; return true;
; template <class Epi, class Sched, bool ALIGN_EPI = false, bool SP2 = false>
; __device__ __forceinline__ void gemm_phase(PG8_LAS unsigned char* lds, const Gemm g, const Sched& S, const Epi& E) {
;     ...
; #pragma unroll
;         for (int a = 0; a < 2; ++a)
; #pragma unroll
;             for (int b = 0; b < 2; ++b)
; #pragma unroll
;                 for (int m = 0; m < 4; ++m)
; #pragma unroll
;                     for (int n = 0; n < 2; ++n) acc[a][b][m][n] = (f32x4){0.f, 0.f, 0.f, 0.f};
;         }
;         cur = nxt; cA = nA; cB = nB; ++ui;
;         if constexpr (ALIGN_EPI) { if (wr == 1) PG8_BAR; }
.Lt2_199:
	s_ashr_i32 s51, s50, 31
	s_lshl_b64 s[18:19], s[50:51], 19
	s_add_u32 s52, s23, s18
	s_addc_u32 s53, s62, s19
	s_and_b64 s[18:19], s[40:41], exec
	s_cselect_b32 s18, s53, s57
	s_cselect_b32 s19, s52, s56
	s_ashr_i32 s49, s48, 31
	s_lshl_b64 s[54:55], s[48:49], 19
	s_add_u32 s54, s14, s54
	s_addc_u32 s55, s22, s55
	s_and_b64 s[60:61], s[40:41], exec
	s_cselect_b32 s20, s55, s59
	s_cselect_b32 s43, s54, s58
	s_add_u32 s56, s56, 0x40080
	s_addc_u32 s57, s57, 0
	s_add_u32 s49, s58, 0x100
	v_mov_b32_e32 v0, 0
	s_addc_u32 s51, s59, 0
	s_mov_b32 s76, -2
	v_mov_b64_e32 v[0:1], 0
	v_mov_b64_e32 v[2:3], 0
	v_mov_b64_e32 v[4:5], 0
	v_mov_b64_e32 v[6:7], 0
	v_mov_b64_e32 v[12:13], 0
	v_mov_b64_e32 v[14:15], 0
	v_mov_b64_e32 v[20:21], 0
	v_mov_b64_e32 v[22:23], 0
	v_mov_b64_e32 v[28:29], 0
	v_mov_b64_e32 v[30:31], 0
	v_mov_b64_e32 v[36:37], 0
	v_mov_b64_e32 v[38:39], 0
	v_mov_b64_e32 v[44:45], 0
	v_mov_b64_e32 v[46:47], 0
	v_mov_b64_e32 v[52:53], 0
	v_mov_b64_e32 v[54:55], 0
	v_mov_b64_e32 v[8:9], 0
	v_mov_b64_e32 v[10:11], 0
	v_mov_b64_e32 v[16:17], 0
	v_mov_b64_e32 v[18:19], 0
	v_mov_b64_e32 v[24:25], 0
	v_mov_b64_e32 v[26:27], 0
	v_mov_b64_e32 v[32:33], 0
	v_mov_b64_e32 v[34:35], 0
	v_mov_b64_e32 v[40:41], 0
	v_mov_b64_e32 v[42:43], 0
	v_mov_b64_e32 v[48:49], 0
	v_mov_b64_e32 v[50:51], 0
	v_mov_b64_e32 v[56:57], 0
	v_mov_b64_e32 v[58:59], 0
	v_mov_b64_e32 v[60:61], 0
	v_mov_b64_e32 v[62:63], 0
	v_mov_b64_e32 v[64:65], 0
	v_mov_b64_e32 v[66:67], 0
	v_mov_b64_e32 v[68:69], 0
	v_mov_b64_e32 v[70:71], 0
	v_mov_b64_e32 v[76:77], 0
	v_mov_b64_e32 v[78:79], 0
	v_mov_b64_e32 v[84:85], 0
	v_mov_b64_e32 v[86:87], 0
	v_mov_b64_e32 v[92:93], 0
	v_mov_b64_e32 v[94:95], 0
	v_mov_b64_e32 v[100:101], 0
	v_mov_b64_e32 v[102:103], 0
	v_mov_b64_e32 v[108:109], 0
	v_mov_b64_e32 v[110:111], 0
	v_mov_b64_e32 v[116:117], 0
	v_mov_b64_e32 v[118:119], 0
	v_mov_b64_e32 v[72:73], 0
	v_mov_b64_e32 v[74:75], 0
	v_mov_b64_e32 v[80:81], 0
	v_mov_b64_e32 v[82:83], 0
	v_mov_b64_e32 v[88:89], 0
	v_mov_b64_e32 v[90:91], 0
	v_mov_b64_e32 v[96:97], 0
	v_mov_b64_e32 v[98:99], 0
	v_mov_b64_e32 v[104:105], 0
	v_mov_b64_e32 v[106:107], 0
	v_mov_b64_e32 v[112:113], 0
	v_mov_b64_e32 v[114:115], 0
	v_mov_b64_e32 v[120:121], 0
	v_mov_b64_e32 v[122:123], 0
	v_mov_b64_e32 v[124:125], 0
	v_mov_b64_e32 v[126:127], 0
	s_andn2_b64 vcc, exec, s[34:35]
	s_cbranch_vccnz .Lt2_nb
	s_barrier
.Lt2_nb:
	s_branch .LBB0_200
.LBB0_193:
	s_add_i32 s74, s74, 1
	s_mul_i32 s10, s74, s33
	s_mul_hi_u32 s11, s74, s86
	s_add_i32 s11, s11, s10
	s_mul_i32 s10, s74, s86
	s_add_u32 s52, s10, s97
	s_addc_u32 s53, s11, s8
	v_mov_b64_e32 v[0:1], 0x800
	v_cmp_lt_i64_e64 s[40:41], s[52:53], v[0:1]
	v_mov_b64_e32 v[0:1], 0x7ff
	v_cmp_gt_i64_e32 vcc, s[52:53], v[0:1]
	s_cbranch_vccnz .LBB0_199
	s_ashr_i32 s10, s52, 31
	s_lshr_b32 s10, s10, 29
	s_add_i32 s18, s52, s10
	s_and_b32 s10, s18, -8
	s_sub_i32 s19, s52, s10
	s_cmp_gt_i32 s19, -1
	s_mov_b64 s[48:49], -1
	s_cbranch_scc0 .LBB0_196
	s_lshl_b32 s20, s19, 8
	s_mov_b64 s[48:49], 0

; __device__ __forceinline__ u32x4 pack8(const f32x4& a, const f32x4& b) { u32x4 w; w.x = pk2(a[0], a[1]); w.y = pk2(a[2], a[3]); w.z = pk2(b[0], b[1]); w.w = pk2(b[2], b[3]); return w; }
;     __device__ __forceinline__ void operator()(const f32x4 (&acc)[2][2][4][2], const Unit& u, int wr, int wc, int fr, int fq) const {
;     ...
;             const int head = (T & 1) * 4 + wc; bf16_t* dst = (T < 2) ? Q : K; const float* g = (T < 2) ? qg : kg; const float sc = (T < 2) ? 0.125f : 1.0f;
;             f32x4 gv[2][2];
; #pragma unroll
;             for (int bj = 0; bj < 2; ++bj)
; #pragma unroll
;                 for (int n = 0; n < 2; ++n) gv[bj][n] = *(const f32x4*)(g + 32 * bj + 8 * fq + 4 * n);
; #pragma unroll
;             for (int ai = 0; ai < 2; ++ai)
; #pragma unroll
;                 for (int m = 0; m < 4; ++m) {
;                     float ss = 0.f;
; #pragma unroll
;                     for (int bj = 0; bj < 2; ++bj)
; #pragma unroll
;                         for (int n = 0; n < 2; ++n) { const f32x4 x = acc[ai][bj][m][n]; ss += (x[0] * x[0] + x[1] * x[1]) + (x[2] * x[2] + x[3] * x[3]); }
;                     ss += __shfl_xor(ss, 16); ss += __shfl_xor(ss, 32);
;                     const float rs = rsqrtf(ss * rx[ai][m] * rx[ai][m] * (1.0f / 64.0f) + EPS) * rx[ai][m] * sc;
;                     bf16_t* rowp = dst + (size_t)(lrow0 + ai * HALF + m * 16) * 512 + head * 64 + 8 * fq;
; #pragma unroll
;                     for (int bj = 0; bj < 2; ++bj) { const f32x4 v0 = acc[ai][bj][m][0] * rs * gv[bj][0], v1 = acc[ai][bj][m][1] * rs * gv[bj][1]; *(u32x4*)(rowp + 32 * bj) = pack8(v0, v1); }
.LBB0_215:
	s_lshl_b32 s10, s75, 2
	s_and_b32 s18, s10, 4
	s_cmp_lt_i32 s75, 2
	s_cselect_b64 vcc, -1, 0
	s_and_b64 s[42:43], vcc, exec
	s_cselect_b32 s10, 0, 0x400000
	s_cselect_b32 s11, s28, s30
	s_cselect_b32 s19, s29, s31
	s_add_u32 s10, s49, s10
	s_addc_u32 s20, s51, 0
	s_add_u32 s42, s11, s46
	v_mov_b32_e32 v128, 0x3e000000
	s_addc_u32 s43, s19, s47
	v_lshlrev_b32_e32 v175, 2, v152
	v_cndmask_b32_e32 v173, 1.0, v128, vcc
	global_load_dwordx4 v[136:139], v175, s[42:43]
	global_load_dwordx4 v[132:135], v175, s[42:43] offset:16
	global_load_dwordx4 v[128:131], v175, s[42:43] offset:128
	v_pk_mul_f32 v[140:141], v[126:127], v[126:127]
	v_pk_mul_f32 v[178:179], v[124:125], v[124:125]
	v_pk_mul_f32 v[142:143], v[122:123], v[122:123]
	v_pk_mul_f32 v[180:181], v[120:121], v[120:121]
	v_pk_mov_b32 v[196:197], v[178:179], v[140:141] op_sel:[1,0]
	v_mov_b32_e32 v179, v141
	v_pk_mov_b32 v[198:199], v[180:181], v[142:143] op_sel:[1,0]
	v_mov_b32_e32 v181, v143
	global_load_dwordx4 v[140:143], v175, s[42:43] offset:144
	v_mul_f32_e32 v182, v117, v117
	v_mul_f32_e32 v184, v119, v119
	v_pk_add_f32 v[178:179], v[196:197], v[178:179]
	v_pk_add_f32 v[180:181], v[198:199], v[180:181]
	v_mul_f32_e32 v177, v108, v108
	v_mul_f32_e32 v200, v109, v109
	v_mul_f32_e32 v201, v110, v110
	v_mul_f32_e32 v202, v111, v111
	v_pk_fma_f32 v[182:183], v[116:117], v[116:117], v[182:183] op_sel_hi:[1,1,0]
	v_pk_fma_f32 v[184:185], v[118:119], v[118:119], v[184:185] op_sel_hi:[1,1,0]
	v_pk_add_f32 v[178:179], v[178:179], v[178:179] op_sel:[0,1] op_sel_hi:[1,0]
	v_pk_add_f32 v[180:181], v[180:181], v[180:181] op_sel:[0,1] op_sel_hi:[1,0]
	v_mov_b32_e32 v183, v201
	v_mov_b32_e32 v185, v202
	v_mov_b32_e32 v179, v177
	v_mov_b32_e32 v181, v200
	v_pk_add_f32 v[182:183], v[182:183], v[184:185]
	v_pk_add_f32 v[178:179], v[178:179], v[180:181]
	s_or_b32 s11, s18, s68
	v_pk_add_f32 v[178:179], v[178:179], v[182:183]
	s_lshl_b32 s11, s11, 7
	v_add_f32_e32 v175, v178, v179
	ds_bpermute_b32 v177, v169, v175
	v_pk_mul_f32 v[186:187], v[114:115], v[114:115]
	v_pk_mul_f32 v[188:189], v[112:113], v[112:113]
	s_add_u32 s18, s10, s11
	v_lshlrev_b32_e32 v192, 1, v152
	s_waitcnt lgkmcnt(0)
	v_add_f32_e32 v175, v175, v177
	ds_bpermute_b32 v177, v167, v175
	v_pk_mov_b32 v[178:179], v[188:189], v[186:187] op_sel:[1,0]
	v_mov_b32_e32 v189, v187
	s_addc_u32 s19, s20, 0
	v_pk_add_f32 v[182:183], v[178:179], v[188:189]
	s_waitcnt lgkmcnt(0)
	v_add_f32_e32 v175, v175, v177
	v_mul_f32_e32 v175, v170, v175
	v_mul_f32_e32 v175, v170, v175
	v_fmamk_f32 v175, v175, 0x3c800000, v227
	v_mul_f32_e32 v177, 0x4b800000, v175
	v_cmp_gt_f32_e32 vcc, s99, v175
	v_lshl_add_u64 v[178:179], s[18:19], 0, v[192:193]
	v_lshlrev_b32_e32 v192, 10, v171
	v_cndmask_b32_e32 v175, v175, v177, vcc
	v_rsq_f32_e32 v175, v175
	v_pk_mul_f32 v[190:191], v[106:107], v[106:107]
	v_pk_mul_f32 v[194:195], v[104:105], v[104:105]
	v_lshl_add_u64 v[178:179], v[178:179], 0, v[192:193]
	v_mul_f32_e32 v171, 0x45800000, v175
	v_cndmask_b32_e32 v171, v175, v171, vcc
	v_mul_f32_e32 v170, v170, v171
	v_mul_f32_e32 v170, v173, v170
	v_pk_mul_f32 v[124:125], v[124:125], v[170:171] op_sel_hi:[1,0]
	v_pk_mul_f32 v[126:127], v[126:127], v[170:171] op_sel_hi:[1,0]
	v_pk_mul_f32 v[120:121], v[120:121], v[170:171] op_sel_hi:[1,0]
	v_pk_mul_f32 v[122:123], v[122:123], v[170:171] op_sel_hi:[1,0]
	v_pk_mul_f32 v[184:185], v[116:117], v[170:171] op_sel_hi:[1,0]
	v_pk_mul_f32 v[116:117], v[118:119], v[170:171] op_sel_hi:[1,0]
	v_pk_mov_b32 v[180:181], v[194:195], v[190:191] op_sel:[1,0]
	v_mov_b32_e32 v195, v191
	v_pk_mul_f32 v[108:109], v[108:109], v[170:171] op_sel_hi:[1,0]
	v_pk_mul_f32 v[110:111], v[110:111], v[170:171] op_sel_hi:[1,0]
	s_mov_b32 s4, 0x8000
	s_waitcnt vmcnt(3)
	v_pk_mul_f32 v[118:119], v[138:139], v[126:127]
	v_pk_mul_f32 v[124:125], v[136:137], v[124:125]
	s_waitcnt vmcnt(2)
	v_pk_mul_f32 v[122:123], v[134:135], v[122:123]
	v_pk_mul_f32 v[120:121], v[132:133], v[120:121]
	s_waitcnt vmcnt(1)
	v_pk_mul_f32 v[126:127], v[130:131], v[116:117]
	v_cvt_pk_bf16_f32 v116, v124, v125
	v_cvt_pk_bf16_f32 v117, v118, v119
	v_cvt_pk_bf16_f32 v118, v120, v121
	v_cvt_pk_bf16_f32 v119, v122, v123
	global_store_dwordx4 v[178:179], v[116:119], off
	v_mul_f32_e32 v120, v92, v92
	v_mul_f32_e32 v121, v93, v93
	v_pk_add_f32 v[116:117], v[180:181], v[194:195]
	v_pk_add_f32 v[118:119], v[182:183], v[182:183] op_sel:[0,1] op_sel_hi:[1,0]
	v_pk_add_f32 v[116:117], v[116:117], v[116:117] op_sel:[0,1] op_sel_hi:[1,0]
	v_mov_b32_e32 v119, v120
	v_mov_b32_e32 v117, v121
	v_pk_add_f32 v[116:117], v[118:119], v[116:117]
	v_mul_f32_e32 v118, v101, v101
	v_mul_f32_e32 v120, v103, v103
	v_mul_f32_e32 v122, v94, v94
	v_mul_f32_e32 v123, v95, v95
	v_pk_fma_f32 v[118:119], v[100:101], v[100:101], v[118:119] op_sel_hi:[1,1,0]
	v_pk_fma_f32 v[120:121], v[102:103], v[102:103], v[120:121] op_sel_hi:[1,1,0]
	v_mov_b32_e32 v119, v122
	v_mov_b32_e32 v121, v123
	v_pk_add_f32 v[118:119], v[118:119], v[120:121]
	s_nop 0
	v_pk_add_f32 v[116:117], v[116:117], v[118:119]
	s_waitcnt vmcnt(1)
	v_pk_mul_f32 v[118:119], v[142:143], v[110:111]
	v_add_f32_e32 v120, v116, v117
	ds_bpermute_b32 v121, v169, v120
	v_pk_mul_f32 v[110:111], v[140:141], v[108:109]
	v_pk_mul_f32 v[116:117], v[128:129], v[184:185]
	v_cvt_pk_bf16_f32 v110, v110, v111
	v_cvt_pk_bf16_f32 v108, v116, v117
	s_waitcnt lgkmcnt(0)
	v_add_f32_e32 v120, v120, v121
	ds_bpermute_b32 v121, v167, v120
	v_cvt_pk_bf16_f32 v109, v126, v127
	s_waitcnt lgkmcnt(0)
; __device__ __forceinline__ u32x4 pack8(const f32x4& a, const f32x4& b) { u32x4 w; w.x = pk2(a[0], a[1]); w.y = pk2(a[2], a[3]); w.z = pk2(b[0], b[1]); w.w = pk2(b[2], b[3]); return w; }
;     __device__ __forceinline__ void operator()(const f32x4 (&acc)[2][2][4][2], const Unit& u, int wr, int wc, int fr, int fq) const {
;     ...
;             for (int ai = 0; ai < 2; ++ai)
; #pragma unroll
;                 for (int m = 0; m < 4; ++m) {
;                     float ss = 0.f;
; #pragma unroll
;                     for (int bj = 0; bj < 2; ++bj)
; #pragma unroll
;                         for (int n = 0; n < 2; ++n) { const f32x4 x = acc[ai][bj][m][n]; ss += (x[0] * x[0] + x[1] * x[1]) + (x[2] * x[2] + x[3] * x[3]); }
;                     ss += __shfl_xor(ss, 16); ss += __shfl_xor(ss, 32);
;                     const float rs = rsqrtf(ss * rx[ai][m] * rx[ai][m] * (1.0f / 64.0f) + EPS) * rx[ai][m] * sc;
;                     bf16_t* rowp = dst + (size_t)(lrow0 + ai * HALF + m * 16) * 512 + head * 64 + 8 * fq;
; #pragma unroll
;                     for (int bj = 0; bj < 2; ++bj) { const f32x4 v0 = acc[ai][bj][m][0] * rs * gv[bj][0], v1 = acc[ai][bj][m][1] * rs * gv[bj][1]; *(u32x4*)(rowp + 32 * bj) = pack8(v0, v1); }
	v_add_f32_e32 v111, v120, v121
	v_mul_f32_e32 v111, v166, v111
	v_mul_f32_e32 v111, v166, v111
	v_fmamk_f32 v111, v111, 0x3c800000, v227
	v_mul_f32_e32 v116, 0x4b800000, v111
	v_cmp_gt_f32_e32 vcc, s99, v111
	s_nop 1
	v_cndmask_b32_e32 v111, v111, v116, vcc
	v_rsq_f32_e32 v116, v111
	v_cvt_pk_bf16_f32 v111, v118, v119
	global_store_dwordx4 v[178:179], v[108:111], off offset:64
	s_nop 1
	v_mul_f32_e32 v108, 0x45800000, v116
	v_cndmask_b32_e32 v108, v116, v108, vcc
	v_mul_f32_e32 v108, v166, v108
	v_mul_f32_e32 v108, v173, v108
	v_pk_mul_f32 v[110:111], v[112:113], v[108:109] op_sel_hi:[1,0]
	v_pk_mul_f32 v[112:113], v[114:115], v[108:109] op_sel_hi:[1,0]
	v_pk_mul_f32 v[110:111], v[136:137], v[110:111]
	v_pk_mul_f32 v[104:105], v[104:105], v[108:109] op_sel_hi:[1,0]
	v_pk_mul_f32 v[106:107], v[106:107], v[108:109] op_sel_hi:[1,0]
	v_pk_mul_f32 v[112:113], v[138:139], v[112:113]
	v_pk_mul_f32 v[114:115], v[134:135], v[106:107]
	v_pk_mul_f32 v[106:107], v[132:133], v[104:105]
	v_cvt_pk_bf16_f32 v104, v110, v111
	v_add_co_u32_e32 v110, vcc, s83, v178
	v_cvt_pk_bf16_f32 v105, v112, v113
	v_cvt_pk_bf16_f32 v106, v106, v107
	v_cvt_pk_bf16_f32 v107, v114, v115
	v_addc_co_u32_e32 v111, vcc, 0, v179, vcc
	global_store_dwordx4 v[110:111], v[104:107], off
	v_pk_mul_f32 v[100:101], v[100:101], v[108:109] op_sel_hi:[1,0]
	v_pk_mul_f32 v[102:103], v[102:103], v[108:109] op_sel_hi:[1,0]
	v_pk_mul_f32 v[104:105], v[98:99], v[98:99]
	v_pk_mul_f32 v[106:107], v[96:97], v[96:97]
	v_mul_f32_e32 v109, v76, v76
	v_pk_mov_b32 v[112:113], v[106:107], v[104:105] op_sel:[1,0]
	v_mov_b32_e32 v107, v105
	v_pk_add_f32 v[104:105], v[112:113], v[106:107]
	v_pk_mul_f32 v[106:107], v[90:91], v[90:91]
	v_pk_mul_f32 v[112:113], v[88:89], v[88:89]
	v_pk_add_f32 v[104:105], v[104:105], v[104:105] op_sel:[0,1] op_sel_hi:[1,0]
	v_pk_mov_b32 v[114:115], v[112:113], v[106:107] op_sel:[1,0]
	v_mov_b32_e32 v113, v107
	v_pk_add_f32 v[106:107], v[114:115], v[112:113]
	v_mul_f32_e32 v112, v77, v77
	v_pk_add_f32 v[106:107], v[106:107], v[106:107] op_sel:[0,1] op_sel_hi:[1,0]
	v_mov_b32_e32 v105, v109
	v_mov_b32_e32 v107, v112
	v_pk_add_f32 v[104:105], v[104:105], v[106:107]
	v_mul_f32_e32 v106, v85, v85
	v_mul_f32_e32 v113, v78, v78
	v_pk_fma_f32 v[106:107], v[84:85], v[84:85], v[106:107] op_sel_hi:[1,1,0]
	v_mul_f32_e32 v112, v87, v87
	v_mul_f32_e32 v114, v79, v79
	v_mov_b32_e32 v107, v113
	v_pk_fma_f32 v[112:113], v[86:87], v[86:87], v[112:113] op_sel_hi:[1,1,0]
	v_pk_mul_f32 v[92:93], v[92:93], v[108:109] op_sel_hi:[1,0]
	v_mov_b32_e32 v113, v114
	v_pk_add_f32 v[106:107], v[106:107], v[112:113]
	v_pk_mul_f32 v[94:95], v[94:95], v[108:109] op_sel_hi:[1,0]
	v_pk_add_f32 v[104:105], v[104:105], v[106:107]
	v_pk_mul_f32 v[100:101], v[128:129], v[100:101]
	v_add_f32_e32 v106, v104, v105
	ds_bpermute_b32 v107, v169, v106
	v_pk_mul_f32 v[104:105], v[142:143], v[94:95]
	v_pk_mul_f32 v[94:95], v[140:141], v[92:93]
	v_cvt_pk_bf16_f32 v92, v100, v101
	v_cvt_pk_bf16_f32 v94, v94, v95
	s_waitcnt lgkmcnt(0)
	v_add_f32_e32 v106, v106, v107
	ds_bpermute_b32 v107, v167, v106
	v_pk_mul_f32 v[102:103], v[130:131], v[102:103]
	s_waitcnt lgkmcnt(0)
	v_add_f32_e32 v95, v106, v107
	v_mul_f32_e32 v95, v172, v95
	v_mul_f32_e32 v95, v172, v95
	v_fmamk_f32 v95, v95, 0x3c800000, v227
	v_mul_f32_e32 v100, 0x4b800000, v95
	v_cmp_gt_f32_e32 vcc, s99, v95
	v_cvt_pk_bf16_f32 v93, v102, v103
	s_nop 0
	v_cndmask_b32_e32 v95, v95, v100, vcc
	v_rsq_f32_e32 v100, v95
	v_cvt_pk_bf16_f32 v95, v104, v105
	global_store_dwordx4 v[110:111], v[92:95], off offset:64
	s_nop 1
	v_mul_f32_e32 v92, 0x45800000, v100
	v_cndmask_b32_e32 v92, v100, v92, vcc
	v_mul_f32_e32 v92, v172, v92
	v_mul_f32_e32 v92, v173, v92
	v_pk_mul_f32 v[94:95], v[96:97], v[92:93] op_sel_hi:[1,0]
	v_pk_mul_f32 v[96:97], v[98:99], v[92:93] op_sel_hi:[1,0]
	v_pk_mul_f32 v[94:95], v[136:137], v[94:95]
	v_pk_mul_f32 v[88:89], v[88:89], v[92:93] op_sel_hi:[1,0]
	v_pk_mul_f32 v[90:91], v[90:91], v[92:93] op_sel_hi:[1,0]
	v_pk_mul_f32 v[96:97], v[138:139], v[96:97]
	v_pk_mul_f32 v[98:99], v[134:135], v[90:91]
	v_pk_mul_f32 v[90:91], v[132:133], v[88:89]
	v_cvt_pk_bf16_f32 v88, v94, v95
	v_add_co_u32_e32 v94, vcc, s4, v178
	v_cvt_pk_bf16_f32 v89, v96, v97
	v_cvt_pk_bf16_f32 v90, v90, v91
	v_cvt_pk_bf16_f32 v91, v98, v99
	v_addc_co_u32_e32 v95, vcc, 0, v179, vcc
	global_store_dwordx4 v[94:95], v[88:91], off
	v_pk_mul_f32 v[84:85], v[84:85], v[92:93] op_sel_hi:[1,0]
	v_pk_mul_f32 v[86:87], v[86:87], v[92:93] op_sel_hi:[1,0]
	v_pk_mul_f32 v[88:89], v[82:83], v[82:83]
	v_pk_mul_f32 v[90:91], v[80:81], v[80:81]
	v_mul_f32_e32 v93, v64, v64
	v_pk_mov_b32 v[96:97], v[90:91], v[88:89] op_sel:[1,0]
	v_mov_b32_e32 v91, v89
	v_pk_add_f32 v[88:89], v[96:97], v[90:91]
	v_pk_mul_f32 v[90:91], v[74:75], v[74:75]
	v_pk_mul_f32 v[96:97], v[72:73], v[72:73]
	v_pk_add_f32 v[88:89], v[88:89], v[88:89] op_sel:[0,1] op_sel_hi:[1,0]
	v_pk_mov_b32 v[98:99], v[96:97], v[90:91] op_sel:[1,0]
	v_mov_b32_e32 v97, v91
	v_pk_add_f32 v[90:91], v[98:99], v[96:97]
	v_mul_f32_e32 v96, v65, v65
	v_pk_add_f32 v[90:91], v[90:91], v[90:91] op_sel:[0,1] op_sel_hi:[1,0]
	v_mov_b32_e32 v89, v93
	v_mov_b32_e32 v91, v96
	v_pk_add_f32 v[88:89], v[88:89], v[90:91]
	v_mul_f32_e32 v90, v69, v69
	v_mul_f32_e32 v97, v66, v66
	v_pk_fma_f32 v[90:91], v[68:69], v[68:69], v[90:91] op_sel_hi:[1,1,0]
	v_mul_f32_e32 v96, v71, v71
	v_mul_f32_e32 v98, v67, v67
	v_mov_b32_e32 v91, v97
	v_pk_fma_f32 v[96:97], v[70:71], v[70:71], v[96:97] op_sel_hi:[1,1,0]
	v_pk_mul_f32 v[76:77], v[76:77], v[92:93] op_sel_hi:[1,0]
	v_mov_b32_e32 v97, v98
	v_pk_add_f32 v[90:91], v[90:91], v[96:97]
	v_pk_mul_f32 v[78:79], v[78:79], v[92:93] op_sel_hi:[1,0]
	v_pk_add_f32 v[88:89], v[88:89], v[90:91]
	v_pk_mul_f32 v[84:85], v[128:129], v[84:85]
	v_add_f32_e32 v90, v88, v89
	ds_bpermute_b32 v91, v169, v90
	v_pk_mul_f32 v[88:89], v[142:143], v[78:79]
	v_pk_mul_f32 v[78:79], v[140:141], v[76:77]
	v_cvt_pk_bf16_f32 v76, v84, v85
	v_cvt_pk_bf16_f32 v78, v78, v79
	s_waitcnt lgkmcnt(0)
; __device__ __forceinline__ u32x4 pack8(const f32x4& a, const f32x4& b) { u32x4 w; w.x = pk2(a[0], a[1]); w.y = pk2(a[2], a[3]); w.z = pk2(b[0], b[1]); w.w = pk2(b[2], b[3]); return w; }
;     __device__ __forceinline__ void operator()(const f32x4 (&acc)[2][2][4][2], const Unit& u, int wr, int wc, int fr, int fq) const {
;     ...
;             for (int ai = 0; ai < 2; ++ai)
; #pragma unroll
;                 for (int m = 0; m < 4; ++m) {
;                     float ss = 0.f;
; #pragma unroll
;                     for (int bj = 0; bj < 2; ++bj)
; #pragma unroll
;                         for (int n = 0; n < 2; ++n) { const f32x4 x = acc[ai][bj][m][n]; ss += (x[0] * x[0] + x[1] * x[1]) + (x[2] * x[2] + x[3] * x[3]); }
;                     ss += __shfl_xor(ss, 16); ss += __shfl_xor(ss, 32);
;                     const float rs = rsqrtf(ss * rx[ai][m] * rx[ai][m] * (1.0f / 64.0f) + EPS) * rx[ai][m] * sc;
;                     bf16_t* rowp = dst + (size_t)(lrow0 + ai * HALF + m * 16) * 512 + head * 64 + 8 * fq;
; #pragma unroll
;                     for (int bj = 0; bj < 2; ++bj) { const f32x4 v0 = acc[ai][bj][m][0] * rs * gv[bj][0], v1 = acc[ai][bj][m][1] * rs * gv[bj][1]; *(u32x4*)(rowp + 32 * bj) = pack8(v0, v1); }
	v_add_f32_e32 v90, v90, v91
	ds_bpermute_b32 v91, v167, v90
	v_pk_mul_f32 v[86:87], v[130:131], v[86:87]
	s_mov_b32 s4, 0xc000
	v_cvt_pk_bf16_f32 v77, v86, v87
	s_waitcnt lgkmcnt(0)
	v_add_f32_e32 v79, v90, v91
	v_mul_f32_e32 v79, v164, v79
	v_mul_f32_e32 v79, v164, v79
	v_fmamk_f32 v79, v79, 0x3c800000, v227
	v_mul_f32_e32 v84, 0x4b800000, v79
	v_cmp_gt_f32_e32 vcc, s99, v79
	s_nop 1
	v_cndmask_b32_e32 v79, v79, v84, vcc
	v_rsq_f32_e32 v84, v79
	v_cvt_pk_bf16_f32 v79, v88, v89
	global_store_dwordx4 v[94:95], v[76:79], off offset:64
	s_nop 1
	v_mul_f32_e32 v76, 0x45800000, v84
	v_cndmask_b32_e32 v76, v84, v76, vcc
	v_mul_f32_e32 v76, v164, v76
	v_mul_f32_e32 v76, v173, v76
	v_pk_mul_f32 v[78:79], v[80:81], v[76:77] op_sel_hi:[1,0]
	v_pk_mul_f32 v[80:81], v[82:83], v[76:77] op_sel_hi:[1,0]
	v_pk_mul_f32 v[78:79], v[136:137], v[78:79]
	v_pk_mul_f32 v[72:73], v[72:73], v[76:77] op_sel_hi:[1,0]
	v_pk_mul_f32 v[74:75], v[74:75], v[76:77] op_sel_hi:[1,0]
	v_pk_mul_f32 v[80:81], v[138:139], v[80:81]
	v_pk_mul_f32 v[82:83], v[134:135], v[74:75]
	v_pk_mul_f32 v[74:75], v[132:133], v[72:73]
	v_cvt_pk_bf16_f32 v72, v78, v79
	v_add_co_u32_e32 v78, vcc, s4, v178
	v_cvt_pk_bf16_f32 v73, v80, v81
	v_cvt_pk_bf16_f32 v74, v74, v75
	v_cvt_pk_bf16_f32 v75, v82, v83
	v_addc_co_u32_e32 v79, vcc, 0, v179, vcc
	global_store_dwordx4 v[78:79], v[72:75], off
	v_pk_mul_f32 v[68:69], v[68:69], v[76:77] op_sel_hi:[1,0]
	v_pk_mul_f32 v[70:71], v[70:71], v[76:77] op_sel_hi:[1,0]
	v_pk_mul_f32 v[72:73], v[62:63], v[62:63]
	v_pk_mul_f32 v[74:75], v[60:61], v[60:61]
	v_mul_f32_e32 v77, v44, v44
	v_pk_mov_b32 v[80:81], v[74:75], v[72:73] op_sel:[1,0]
	v_mov_b32_e32 v75, v73
	v_pk_add_f32 v[72:73], v[80:81], v[74:75]
	v_pk_mul_f32 v[74:75], v[58:59], v[58:59]
	v_pk_mul_f32 v[80:81], v[56:57], v[56:57]
	v_pk_add_f32 v[72:73], v[72:73], v[72:73] op_sel:[0,1] op_sel_hi:[1,0]
	v_pk_mov_b32 v[82:83], v[80:81], v[74:75] op_sel:[1,0]
	v_mov_b32_e32 v81, v75
	v_pk_add_f32 v[74:75], v[82:83], v[80:81]
	v_mul_f32_e32 v80, v45, v45
	v_pk_add_f32 v[74:75], v[74:75], v[74:75] op_sel:[0,1] op_sel_hi:[1,0]
	v_mov_b32_e32 v73, v77
	v_mov_b32_e32 v75, v80
	v_pk_add_f32 v[72:73], v[72:73], v[74:75]
	v_mul_f32_e32 v74, v53, v53
	v_mul_f32_e32 v81, v46, v46
	v_pk_fma_f32 v[74:75], v[52:53], v[52:53], v[74:75] op_sel_hi:[1,1,0]
	v_mul_f32_e32 v80, v55, v55
	v_mul_f32_e32 v82, v47, v47
	v_mov_b32_e32 v75, v81
	v_pk_fma_f32 v[80:81], v[54:55], v[54:55], v[80:81] op_sel_hi:[1,1,0]
	v_pk_mul_f32 v[64:65], v[64:65], v[76:77] op_sel_hi:[1,0]
	v_mov_b32_e32 v81, v82
	v_pk_add_f32 v[74:75], v[74:75], v[80:81]
	v_pk_mul_f32 v[66:67], v[66:67], v[76:77] op_sel_hi:[1,0]
	v_pk_add_f32 v[72:73], v[72:73], v[74:75]
	v_pk_mul_f32 v[68:69], v[128:129], v[68:69]
	v_add_f32_e32 v74, v72, v73
	ds_bpermute_b32 v75, v169, v74
	v_pk_mul_f32 v[72:73], v[142:143], v[66:67]
	v_pk_mul_f32 v[66:67], v[140:141], v[64:65]
	v_cvt_pk_bf16_f32 v64, v68, v69
	v_cvt_pk_bf16_f32 v66, v66, v67
	s_waitcnt lgkmcnt(0)
	v_add_f32_e32 v74, v74, v75
	ds_bpermute_b32 v75, v167, v74
	v_pk_mul_f32 v[70:71], v[130:131], v[70:71]
	s_mov_b32 s4, 0x20000
	v_cvt_pk_bf16_f32 v65, v70, v71
	s_waitcnt lgkmcnt(0)
	v_add_f32_e32 v67, v74, v75
	v_mul_f32_e32 v67, v168, v67
	v_mul_f32_e32 v67, v168, v67
	v_fmamk_f32 v67, v67, 0x3c800000, v227
	v_mul_f32_e32 v68, 0x4b800000, v67
	v_cmp_gt_f32_e32 vcc, s99, v67
	s_nop 1
	v_cndmask_b32_e32 v67, v67, v68, vcc
	v_rsq_f32_e32 v68, v67
	v_cvt_pk_bf16_f32 v67, v72, v73
	global_store_dwordx4 v[78:79], v[64:67], off offset:64
	s_nop 1
	v_mul_f32_e32 v64, 0x45800000, v68
	v_cndmask_b32_e32 v64, v68, v64, vcc
	v_mul_f32_e32 v64, v168, v64
	v_mul_f32_e32 v64, v173, v64
	v_pk_mul_f32 v[60:61], v[60:61], v[64:65] op_sel_hi:[1,0]
	v_pk_mul_f32 v[62:63], v[62:63], v[64:65] op_sel_hi:[1,0]
	v_pk_mul_f32 v[60:61], v[136:137], v[60:61]
	v_pk_mul_f32 v[56:57], v[56:57], v[64:65] op_sel_hi:[1,0]
	v_pk_mul_f32 v[58:59], v[58:59], v[64:65] op_sel_hi:[1,0]
	v_pk_mul_f32 v[62:63], v[138:139], v[62:63]
	v_pk_mul_f32 v[66:67], v[134:135], v[58:59]
	v_pk_mul_f32 v[58:59], v[132:133], v[56:57]
	v_cvt_pk_bf16_f32 v56, v60, v61
	v_add_co_u32_e32 v60, vcc, s4, v178
	v_cvt_pk_bf16_f32 v57, v62, v63
	v_cvt_pk_bf16_f32 v58, v58, v59
	v_cvt_pk_bf16_f32 v59, v66, v67
	v_addc_co_u32_e32 v61, vcc, 0, v179, vcc
	global_store_dwordx4 v[60:61], v[56:59], off
	v_pk_mul_f32 v[52:53], v[52:53], v[64:65] op_sel_hi:[1,0]
	v_pk_mul_f32 v[54:55], v[54:55], v[64:65] op_sel_hi:[1,0]
	v_pk_mul_f32 v[56:57], v[50:51], v[50:51]
	v_pk_mul_f32 v[58:59], v[48:49], v[48:49]
	v_mul_f32_e32 v65, v30, v30
	v_pk_mov_b32 v[62:63], v[58:59], v[56:57] op_sel:[1,0]
	v_mov_b32_e32 v59, v57
	v_pk_add_f32 v[56:57], v[62:63], v[58:59]
	v_pk_mul_f32 v[58:59], v[42:43], v[42:43]
	v_pk_mul_f32 v[62:63], v[40:41], v[40:41]
	v_pk_add_f32 v[56:57], v[56:57], v[56:57] op_sel:[0,1] op_sel_hi:[1,0]
	v_pk_mov_b32 v[66:67], v[62:63], v[58:59] op_sel:[1,0]
	v_mov_b32_e32 v63, v59
	v_pk_add_f32 v[58:59], v[66:67], v[62:63]
	v_mul_f32_e32 v62, v28, v28
	v_mul_f32_e32 v63, v29, v29
	v_pk_add_f32 v[58:59], v[58:59], v[58:59] op_sel:[0,1] op_sel_hi:[1,0]
	v_mov_b32_e32 v57, v62
	v_mov_b32_e32 v59, v63
	v_pk_add_f32 v[56:57], v[56:57], v[58:59]
	v_mul_f32_e32 v58, v37, v37
	v_mul_f32_e32 v62, v39, v39
	v_mul_f32_e32 v66, v31, v31
	v_pk_fma_f32 v[58:59], v[36:37], v[36:37], v[58:59] op_sel_hi:[1,1,0]
	v_pk_fma_f32 v[62:63], v[38:39], v[38:39], v[62:63] op_sel_hi:[1,1,0]
	v_mov_b32_e32 v59, v65
	v_mov_b32_e32 v63, v66
	v_pk_add_f32 v[58:59], v[58:59], v[62:63]
	v_pk_mul_f32 v[44:45], v[44:45], v[64:65] op_sel_hi:[1,0]
	v_pk_add_f32 v[56:57], v[56:57], v[58:59]
	v_pk_mul_f32 v[46:47], v[46:47], v[64:65] op_sel_hi:[1,0]
	v_add_f32_e32 v58, v56, v57
	ds_bpermute_b32 v59, v169, v58
	v_pk_mul_f32 v[56:57], v[142:143], v[46:47]
	v_pk_mul_f32 v[46:47], v[140:141], v[44:45]
	v_pk_mul_f32 v[52:53], v[128:129], v[52:53]
	v_cvt_pk_bf16_f32 v46, v46, v47
	s_waitcnt lgkmcnt(0)
; __device__ __forceinline__ u32x4 pack8(const f32x4& a, const f32x4& b) { u32x4 w; w.x = pk2(a[0], a[1]); w.y = pk2(a[2], a[3]); w.z = pk2(b[0], b[1]); w.w = pk2(b[2], b[3]); return w; }
;     __device__ __forceinline__ void operator()(const f32x4 (&acc)[2][2][4][2], const Unit& u, int wr, int wc, int fr, int fq) const {
;     ...
;             for (int ai = 0; ai < 2; ++ai)
; #pragma unroll
;                 for (int m = 0; m < 4; ++m) {
;                     float ss = 0.f;
; #pragma unroll
;                     for (int bj = 0; bj < 2; ++bj)
; #pragma unroll
;                         for (int n = 0; n < 2; ++n) { const f32x4 x = acc[ai][bj][m][n]; ss += (x[0] * x[0] + x[1] * x[1]) + (x[2] * x[2] + x[3] * x[3]); }
;                     ss += __shfl_xor(ss, 16); ss += __shfl_xor(ss, 32);
;                     const float rs = rsqrtf(ss * rx[ai][m] * rx[ai][m] * (1.0f / 64.0f) + EPS) * rx[ai][m] * sc;
;                     bf16_t* rowp = dst + (size_t)(lrow0 + ai * HALF + m * 16) * 512 + head * 64 + 8 * fq;
; #pragma unroll
;                     for (int bj = 0; bj < 2; ++bj) { const f32x4 v0 = acc[ai][bj][m][0] * rs * gv[bj][0], v1 = acc[ai][bj][m][1] * rs * gv[bj][1]; *(u32x4*)(rowp + 32 * bj) = pack8(v0, v1); }
	v_add_f32_e32 v58, v58, v59
	ds_bpermute_b32 v59, v167, v58
	v_cvt_pk_bf16_f32 v44, v52, v53
	v_pk_mul_f32 v[54:55], v[130:131], v[54:55]
	s_mov_b32 s4, 0x24000
	v_cvt_pk_bf16_f32 v45, v54, v55
	s_waitcnt lgkmcnt(0)
	v_add_f32_e32 v47, v58, v59
	v_mul_f32_e32 v47, v162, v47
	v_mul_f32_e32 v47, v162, v47
	v_fmamk_f32 v47, v47, 0x3c800000, v227
	v_mul_f32_e32 v52, 0x4b800000, v47
	v_cmp_gt_f32_e32 vcc, s99, v47
	s_nop 1
	v_cndmask_b32_e32 v47, v47, v52, vcc
	v_rsq_f32_e32 v52, v47
	v_cvt_pk_bf16_f32 v47, v56, v57
	global_store_dwordx4 v[60:61], v[44:47], off offset:64
	s_nop 1
	v_mul_f32_e32 v44, 0x45800000, v52
	v_cndmask_b32_e32 v44, v52, v44, vcc
	v_mul_f32_e32 v44, v162, v44
	v_mul_f32_e32 v44, v173, v44
	v_pk_mul_f32 v[46:47], v[48:49], v[44:45] op_sel_hi:[1,0]
	v_pk_mul_f32 v[48:49], v[50:51], v[44:45] op_sel_hi:[1,0]
	v_pk_mul_f32 v[46:47], v[136:137], v[46:47]
	v_pk_mul_f32 v[40:41], v[40:41], v[44:45] op_sel_hi:[1,0]
	v_pk_mul_f32 v[42:43], v[42:43], v[44:45] op_sel_hi:[1,0]
	v_pk_mul_f32 v[48:49], v[138:139], v[48:49]
	v_pk_mul_f32 v[50:51], v[134:135], v[42:43]
	v_pk_mul_f32 v[42:43], v[132:133], v[40:41]
	v_cvt_pk_bf16_f32 v40, v46, v47
	v_add_co_u32_e32 v46, vcc, s4, v178
	v_cvt_pk_bf16_f32 v41, v48, v49
	v_cvt_pk_bf16_f32 v42, v42, v43
	v_cvt_pk_bf16_f32 v43, v50, v51
	v_addc_co_u32_e32 v47, vcc, 0, v179, vcc
	global_store_dwordx4 v[46:47], v[40:43], off
	v_pk_mul_f32 v[36:37], v[36:37], v[44:45] op_sel_hi:[1,0]
	v_pk_mul_f32 v[38:39], v[38:39], v[44:45] op_sel_hi:[1,0]
	v_pk_mul_f32 v[40:41], v[34:35], v[34:35]
	v_pk_mul_f32 v[42:43], v[32:33], v[32:33]
	v_mul_f32_e32 v45, v12, v12
	v_pk_mov_b32 v[48:49], v[42:43], v[40:41] op_sel:[1,0]
	v_mov_b32_e32 v43, v41
	v_pk_add_f32 v[40:41], v[48:49], v[42:43]
	v_pk_mul_f32 v[42:43], v[26:27], v[26:27]
	v_pk_mul_f32 v[48:49], v[24:25], v[24:25]
	v_pk_add_f32 v[40:41], v[40:41], v[40:41] op_sel:[0,1] op_sel_hi:[1,0]
	v_pk_mov_b32 v[50:51], v[48:49], v[42:43] op_sel:[1,0]
	v_mov_b32_e32 v49, v43
	v_pk_add_f32 v[42:43], v[50:51], v[48:49]
	v_mul_f32_e32 v48, v13, v13
	v_pk_add_f32 v[42:43], v[42:43], v[42:43] op_sel:[0,1] op_sel_hi:[1,0]
	v_mov_b32_e32 v41, v45
	v_mov_b32_e32 v43, v48
	v_pk_add_f32 v[40:41], v[40:41], v[42:43]
	v_mul_f32_e32 v42, v21, v21
	v_mul_f32_e32 v49, v14, v14
	v_pk_fma_f32 v[42:43], v[20:21], v[20:21], v[42:43] op_sel_hi:[1,1,0]
	v_mul_f32_e32 v48, v23, v23
	v_mul_f32_e32 v50, v15, v15
	v_mov_b32_e32 v43, v49
	v_pk_fma_f32 v[48:49], v[22:23], v[22:23], v[48:49] op_sel_hi:[1,1,0]
	v_pk_mul_f32 v[28:29], v[28:29], v[44:45] op_sel_hi:[1,0]
	v_mov_b32_e32 v49, v50
	v_pk_add_f32 v[42:43], v[42:43], v[48:49]
	v_pk_mul_f32 v[30:31], v[30:31], v[44:45] op_sel_hi:[1,0]
	v_pk_add_f32 v[40:41], v[40:41], v[42:43]
	v_pk_mul_f32 v[36:37], v[128:129], v[36:37]
	v_add_f32_e32 v42, v40, v41
	ds_bpermute_b32 v43, v169, v42
	v_pk_mul_f32 v[40:41], v[142:143], v[30:31]
	v_pk_mul_f32 v[30:31], v[140:141], v[28:29]
	v_cvt_pk_bf16_f32 v28, v36, v37
	v_cvt_pk_bf16_f32 v30, v30, v31
	s_waitcnt lgkmcnt(0)
	v_add_f32_e32 v42, v42, v43
	ds_bpermute_b32 v43, v167, v42
	v_pk_mul_f32 v[38:39], v[130:131], v[38:39]
	s_mov_b32 s4, 0x28000
	v_cvt_pk_bf16_f32 v29, v38, v39
	s_waitcnt lgkmcnt(0)
; #define PG8_BAR __builtin_amdgcn_s_barrier()
; __device__ __forceinline__ u32x4 pack8(const f32x4& a, const f32x4& b) { u32x4 w; w.x = pk2(a[0], a[1]); w.y = pk2(a[2], a[3]); w.z = pk2(b[0], b[1]); w.w = pk2(b[2], b[3]); return w; }
; template <class Epi, class Sched, bool ALIGN_EPI = false, bool SP2 = false>
; __device__ __forceinline__ void gemm_phase(PG8_LAS unsigned char* lds, const Gemm g, const Sched& S, const Epi& E) {
;     ...
;         if (!has_next) break;
;         if (epi_now) {
; #pragma unroll
;         for (int a = 0; a < 2; ++a)
; #pragma unroll
;             for (int b = 0; b < 2; ++b)
; #pragma unroll
;                 for (int m = 0; m < 4; ++m)
; #pragma unroll
;                     for (int n = 0; n < 2; ++n) acc[a][b][m][n] = (f32x4){0.f, 0.f, 0.f, 0.f};
;         }
;         cur = nxt; cA = nA; cB = nB; ++ui;
;         if constexpr (ALIGN_EPI) { if (wr == 1) PG8_BAR; }
;     __device__ __forceinline__ void operator()(const f32x4 (&acc)[2][2][4][2], const Unit& u, int wr, int wc, int fr, int fq) const {
;     ...
;             for (int ai = 0; ai < 2; ++ai)
; #pragma unroll
;                 for (int m = 0; m < 4; ++m) {
;                     float ss = 0.f;
; #pragma unroll
;                     for (int bj = 0; bj < 2; ++bj)
; #pragma unroll
;                         for (int n = 0; n < 2; ++n) { const f32x4 x = acc[ai][bj][m][n]; ss += (x[0] * x[0] + x[1] * x[1]) + (x[2] * x[2] + x[3] * x[3]); }
;                     ss += __shfl_xor(ss, 16); ss += __shfl_xor(ss, 32);
;                     const float rs = rsqrtf(ss * rx[ai][m] * rx[ai][m] * (1.0f / 64.0f) + EPS) * rx[ai][m] * sc;
;                     bf16_t* rowp = dst + (size_t)(lrow0 + ai * HALF + m * 16) * 512 + head * 64 + 8 * fq;
; #pragma unroll
;                     for (int bj = 0; bj < 2; ++bj) { const f32x4 v0 = acc[ai][bj][m][0] * rs * gv[bj][0], v1 = acc[ai][bj][m][1] * rs * gv[bj][1]; *(u32x4*)(rowp + 32 * bj) = pack8(v0, v1); }
	v_add_f32_e32 v31, v42, v43
	v_mul_f32_e32 v31, v176, v31
	v_mul_f32_e32 v31, v176, v31
	v_fmamk_f32 v31, v31, 0x3c800000, v227
	v_mul_f32_e32 v36, 0x4b800000, v31
	v_cmp_gt_f32_e32 vcc, s99, v31
	s_nop 1
	v_cndmask_b32_e32 v31, v31, v36, vcc
	v_rsq_f32_e32 v36, v31
	v_cvt_pk_bf16_f32 v31, v40, v41
	global_store_dwordx4 v[46:47], v[28:31], off offset:64
	s_nop 1
	v_mul_f32_e32 v28, 0x45800000, v36
	v_cndmask_b32_e32 v28, v36, v28, vcc
	v_mul_f32_e32 v28, v176, v28
	v_mul_f32_e32 v28, v173, v28
	v_pk_mul_f32 v[30:31], v[32:33], v[28:29] op_sel_hi:[1,0]
	v_pk_mul_f32 v[32:33], v[34:35], v[28:29] op_sel_hi:[1,0]
	v_pk_mul_f32 v[30:31], v[136:137], v[30:31]
	v_pk_mul_f32 v[24:25], v[24:25], v[28:29] op_sel_hi:[1,0]
	v_pk_mul_f32 v[26:27], v[26:27], v[28:29] op_sel_hi:[1,0]
	v_pk_mul_f32 v[32:33], v[138:139], v[32:33]
	v_pk_mul_f32 v[34:35], v[134:135], v[26:27]
	v_pk_mul_f32 v[26:27], v[132:133], v[24:25]
	v_cvt_pk_bf16_f32 v24, v30, v31
	v_add_co_u32_e32 v30, vcc, s4, v178
	v_cvt_pk_bf16_f32 v25, v32, v33
	v_cvt_pk_bf16_f32 v26, v26, v27
	v_cvt_pk_bf16_f32 v27, v34, v35
	v_addc_co_u32_e32 v31, vcc, 0, v179, vcc
	global_store_dwordx4 v[30:31], v[24:27], off
	v_pk_mul_f32 v[20:21], v[20:21], v[28:29] op_sel_hi:[1,0]
	v_pk_mul_f32 v[22:23], v[22:23], v[28:29] op_sel_hi:[1,0]
	v_pk_mul_f32 v[24:25], v[18:19], v[18:19]
	v_pk_mul_f32 v[26:27], v[16:17], v[16:17]
	v_mul_f32_e32 v29, v0, v0
	v_pk_mov_b32 v[32:33], v[26:27], v[24:25] op_sel:[1,0]
	v_mov_b32_e32 v27, v25
	v_pk_add_f32 v[24:25], v[32:33], v[26:27]
	v_pk_mul_f32 v[26:27], v[10:11], v[10:11]
	v_pk_mul_f32 v[32:33], v[8:9], v[8:9]
	v_pk_add_f32 v[24:25], v[24:25], v[24:25] op_sel:[0,1] op_sel_hi:[1,0]
	v_pk_mov_b32 v[34:35], v[32:33], v[26:27] op_sel:[1,0]
	v_mov_b32_e32 v33, v27
	v_pk_add_f32 v[26:27], v[34:35], v[32:33]
	v_mul_f32_e32 v32, v1, v1
	v_pk_add_f32 v[26:27], v[26:27], v[26:27] op_sel:[0,1] op_sel_hi:[1,0]
	v_mov_b32_e32 v25, v29
	v_mov_b32_e32 v27, v32
	v_pk_add_f32 v[24:25], v[24:25], v[26:27]
	v_mul_f32_e32 v26, v5, v5
	v_mul_f32_e32 v33, v2, v2
	v_pk_fma_f32 v[26:27], v[4:5], v[4:5], v[26:27] op_sel_hi:[1,1,0]
	v_mul_f32_e32 v32, v7, v7
	v_mul_f32_e32 v34, v3, v3
	v_mov_b32_e32 v27, v33
	v_pk_fma_f32 v[32:33], v[6:7], v[6:7], v[32:33] op_sel_hi:[1,1,0]
	v_pk_mul_f32 v[12:13], v[12:13], v[28:29] op_sel_hi:[1,0]
	v_mov_b32_e32 v33, v34
	v_pk_add_f32 v[26:27], v[26:27], v[32:33]
	v_pk_mul_f32 v[14:15], v[14:15], v[28:29] op_sel_hi:[1,0]
	v_pk_add_f32 v[24:25], v[24:25], v[26:27]
	v_pk_mul_f32 v[20:21], v[128:129], v[20:21]
	v_add_f32_e32 v26, v24, v25
	ds_bpermute_b32 v27, v169, v26
	v_pk_mul_f32 v[24:25], v[142:143], v[14:15]
	v_pk_mul_f32 v[14:15], v[140:141], v[12:13]
	v_cvt_pk_bf16_f32 v12, v20, v21
	v_cvt_pk_bf16_f32 v14, v14, v15
	s_waitcnt lgkmcnt(0)
	v_add_f32_e32 v26, v26, v27
	ds_bpermute_b32 v27, v167, v26
	v_pk_mul_f32 v[22:23], v[130:131], v[22:23]
	s_waitcnt lgkmcnt(0)
	v_add_f32_e32 v15, v26, v27
	v_mul_f32_e32 v15, v174, v15
	v_mul_f32_e32 v15, v174, v15
	v_fmamk_f32 v15, v15, 0x3c800000, v227
	v_mul_f32_e32 v20, 0x4b800000, v15
	v_cmp_gt_f32_e32 vcc, s99, v15
	v_cvt_pk_bf16_f32 v13, v22, v23
	s_nop 0
	v_cndmask_b32_e32 v15, v15, v20, vcc
	v_rsq_f32_e32 v20, v15
	v_cvt_pk_bf16_f32 v15, v24, v25
	global_store_dwordx4 v[30:31], v[12:15], off offset:64
	s_nop 1
	v_mul_f32_e32 v12, 0x45800000, v20
	v_cndmask_b32_e32 v12, v20, v12, vcc
	v_mul_f32_e32 v12, v174, v12
	v_mul_f32_e32 v12, v173, v12
	v_pk_mul_f32 v[14:15], v[16:17], v[12:13] op_sel_hi:[1,0]
	v_pk_mul_f32 v[16:17], v[18:19], v[12:13] op_sel_hi:[1,0]
	v_pk_mul_f32 v[14:15], v[136:137], v[14:15]
	v_pk_mul_f32 v[8:9], v[8:9], v[12:13] op_sel_hi:[1,0]
	v_pk_mul_f32 v[10:11], v[10:11], v[12:13] op_sel_hi:[1,0]
	v_pk_mul_f32 v[16:17], v[138:139], v[16:17]
	v_pk_mul_f32 v[18:19], v[134:135], v[10:11]
	v_pk_mul_f32 v[10:11], v[132:133], v[8:9]
	v_cvt_pk_bf16_f32 v8, v14, v15
	v_add_co_u32_e32 v14, vcc, s5, v178
	v_cvt_pk_bf16_f32 v9, v16, v17
	v_cvt_pk_bf16_f32 v10, v10, v11
	v_cvt_pk_bf16_f32 v11, v18, v19
	v_addc_co_u32_e32 v15, vcc, 0, v179, vcc
	v_pk_mul_f32 v[4:5], v[4:5], v[12:13] op_sel_hi:[1,0]
	v_pk_mul_f32 v[6:7], v[6:7], v[12:13] op_sel_hi:[1,0]
	v_pk_mul_f32 v[0:1], v[0:1], v[12:13] op_sel_hi:[1,0]
	v_pk_mul_f32 v[2:3], v[2:3], v[12:13] op_sel_hi:[1,0]
	global_store_dwordx4 v[14:15], v[8:11], off
	v_pk_mul_f32 v[6:7], v[130:131], v[6:7]
	v_pk_mul_f32 v[4:5], v[128:129], v[4:5]
	v_pk_mul_f32 v[8:9], v[142:143], v[2:3]
	v_pk_mul_f32 v[2:3], v[140:141], v[0:1]
	v_cvt_pk_bf16_f32 v0, v4, v5
	v_cvt_pk_bf16_f32 v1, v6, v7
	v_cvt_pk_bf16_f32 v2, v2, v3
	v_cvt_pk_bf16_f32 v3, v8, v9
	global_store_dwordx4 v[14:15], v[0:3], off offset:64
	s_andn2_b64 vcc, exec, s[40:41]
	s_mov_b64 s[18:19], -1
	s_cbranch_vccnz .LBB0_192
.LBB0_216:
	s_branch .LBB0_191
.LBB0_218:
	s_waitcnt vmcnt(0)
	s_barrier
	s_cmp_lt_i32 s3, 2
	s_mov_b64 s[28:29], -1
	s_cbranch_scc1 .LBB0_177

; #define PG8_BAR __builtin_amdgcn_s_barrier()
;     __device__ __forceinline__ bool next(int i, Unit& u) const { const int r = i / 9, tile = t0 + r * ts; if (r >= nr || tile >= 512) return false; u.pm = tile >> 2; u.pn = tile & 3; u.kind = i % 9; return true; }
;     __host__ __device__ bool next(int i, Unit& u) const {
;         const long L = (long)i * G + c; if (L >= nwg) return false;
;         int wgid = (int)L; { const int q = nwg / NXCD, r = nwg % NXCD, xcd = wgid % NXCD, off = wgid / NXCD; wgid = (xcd < r ? xcd * (q + 1) : r * (q + 1) + (xcd - r) * q) + off; }
;         const int nig = WGM * nN, gid = wgid / nig, fm = gid * WGM, gsz = (nM - fm) < WGM ? (nM - fm) : WGM;
;         u.pm = fm + ((wgid % nig) % gsz); u.pn = (wgid % nig) / gsz; u.kind = 1; return true;
; template <class Epi, class Sched, bool ALIGN_EPI = false, bool SP2 = false>
; __device__ __forceinline__ void gemm_phase(PG8_LAS unsigned char* lds, const Gemm g, const Sched& S, const Epi& E) {
;     ...
; #pragma unroll
;         for (int a = 0; a < 2; ++a)
; #pragma unroll
;             for (int b = 0; b < 2; ++b)
; #pragma unroll
;                 for (int m = 0; m < 4; ++m)
; #pragma unroll
;                     for (int n = 0; n < 2; ++n) acc[a][b][m][n] = (f32x4){0.f, 0.f, 0.f, 0.f};
;         }
;         cur = nxt; cA = nA; cB = nB; ++ui;
;         if constexpr (ALIGN_EPI) { if (wr == 1) PG8_BAR; }
.Lt4_576:
	s_ashr_i32 s29, s28, 31
	s_lshl_b64 s[10:11], s[28:29], 19
	s_add_u32 s30, s3, s10
	s_addc_u32 s31, s8, s11
	s_and_b64 s[10:11], s[40:41], exec
	s_cselect_b32 s29, s31, s45
	s_cselect_b32 s43, s30, s44
	s_ashr_i32 s27, s26, 31
	s_lshl_b64 s[10:11], s[26:27], 19
	s_add_u32 s34, s14, s10
	s_addc_u32 s35, s18, s11
	s_and_b64 s[10:11], s[40:41], exec
	s_cselect_b32 s27, s35, s47
	s_cselect_b32 s60, s34, s46
	s_add_u32 s44, s44, 0x40080
	s_addc_u32 s45, s45, 0
	s_add_u32 s61, s46, 0x100
	v_mov_b32_e32 v0, 0
	s_addc_u32 s62, s47, 0
	s_mov_b32 s63, -2
	v_mov_b64_e32 v[0:1], 0
	v_mov_b64_e32 v[2:3], 0
	v_mov_b64_e32 v[8:9], 0
	v_mov_b64_e32 v[10:11], 0
	v_mov_b64_e32 v[16:17], 0
	v_mov_b64_e32 v[18:19], 0
	v_mov_b64_e32 v[24:25], 0
	v_mov_b64_e32 v[26:27], 0
	v_mov_b64_e32 v[32:33], 0
	v_mov_b64_e32 v[34:35], 0
	v_mov_b64_e32 v[40:41], 0
	v_mov_b64_e32 v[42:43], 0
	v_mov_b64_e32 v[48:49], 0
	v_mov_b64_e32 v[50:51], 0
	v_mov_b64_e32 v[56:57], 0
	v_mov_b64_e32 v[58:59], 0
	v_mov_b64_e32 v[4:5], 0
	v_mov_b64_e32 v[6:7], 0
	v_mov_b64_e32 v[12:13], 0
	v_mov_b64_e32 v[14:15], 0
	v_mov_b64_e32 v[20:21], 0
	v_mov_b64_e32 v[22:23], 0
	v_mov_b64_e32 v[28:29], 0
	v_mov_b64_e32 v[30:31], 0
	v_mov_b64_e32 v[36:37], 0
	v_mov_b64_e32 v[38:39], 0
	v_mov_b64_e32 v[44:45], 0
	v_mov_b64_e32 v[46:47], 0
	v_mov_b64_e32 v[52:53], 0
	v_mov_b64_e32 v[54:55], 0
	v_mov_b64_e32 v[60:61], 0
	v_mov_b64_e32 v[62:63], 0
	v_mov_b64_e32 v[64:65], 0
	v_mov_b64_e32 v[66:67], 0
	v_mov_b64_e32 v[72:73], 0
	v_mov_b64_e32 v[74:75], 0
	v_mov_b64_e32 v[80:81], 0
	v_mov_b64_e32 v[82:83], 0
	v_mov_b64_e32 v[88:89], 0
	v_mov_b64_e32 v[90:91], 0
	v_mov_b64_e32 v[96:97], 0
	v_mov_b64_e32 v[98:99], 0
	v_mov_b64_e32 v[104:105], 0
	v_mov_b64_e32 v[106:107], 0
	v_mov_b64_e32 v[112:113], 0
	v_mov_b64_e32 v[114:115], 0
	v_mov_b64_e32 v[120:121], 0
	v_mov_b64_e32 v[122:123], 0
	v_mov_b64_e32 v[68:69], 0
	v_mov_b64_e32 v[70:71], 0
	v_mov_b64_e32 v[76:77], 0
	v_mov_b64_e32 v[78:79], 0
	v_mov_b64_e32 v[84:85], 0
	v_mov_b64_e32 v[86:87], 0
	v_mov_b64_e32 v[92:93], 0
	v_mov_b64_e32 v[94:95], 0
	v_mov_b64_e32 v[100:101], 0
	v_mov_b64_e32 v[102:103], 0
	v_mov_b64_e32 v[108:109], 0
	v_mov_b64_e32 v[110:111], 0
	v_mov_b64_e32 v[116:117], 0
	v_mov_b64_e32 v[118:119], 0
	v_mov_b64_e32 v[124:125], 0
	v_mov_b64_e32 v[126:127], 0
	s_andn2_b64 vcc, exec, s[22:23]
	s_cbranch_vccnz .Lt4_nb
	s_barrier
.Lt4_nb:
	s_branch .LBB0_577
.LBB0_574:
	s_add_i32 s58, s58, 1
	s_mul_i32 s10, s58, s33
	s_mul_hi_u32 s11, s58, s86
	s_add_i32 s11, s11, s10
	s_mul_i32 s10, s58, s86
	s_add_u32 s30, s10, s97
	s_addc_u32 s31, s11, s50
	v_mov_b64_e32 v[0:1], 0xb00
	v_cmp_lt_i64_e64 s[40:41], s[30:31], v[0:1]
	v_mov_b64_e32 v[0:1], 0xaff
	v_cmp_gt_i64_e32 vcc, s[30:31], v[0:1]
	s_cbranch_vccnz .LBB0_576
	s_ashr_i32 s10, s30, 31
	s_lshr_b32 s10, s10, 29
	s_add_i32 s10, s30, s10
	s_ashr_i32 s11, s10, 3
	s_and_b32 s10, s10, -8
	s_sub_i32 s10, s30, s10
	s_cmp_lt_i32 s10, 0
	s_cselect_b32 s26, s5, 0x160
	s_mul_i32 s10, s10, s26
	s_add_i32 s10, s10, s11
	s_mul_hi_i32 s11, s10, 0x2e8ba2e9
	s_lshr_b32 s26, s11, 31
	s_ashr_i32 s11, s11, 5
	s_add_i32 s11, s11, s26
	s_lshl_b32 s27, s11, 3
	s_sub_i32 s26, 0x80, s27
	s_min_i32 s28, s26, 8
	s_abs_i32 s26, s28
	v_cvt_f32_u32_e32 v0, s26
	s_sub_i32 s30, 0, s26
	s_mulk_i32 s11, 0xb0
	s_sub_i32 s10, s10, s11
	v_rcp_iflag_f32_e32 v0, v0
	s_abs_i32 s11, s10
	s_xor_b32 s29, s10, s28
	s_ashr_i32 s29, s29, 31
	v_mul_f32_e32 v0, 0x4f7ffffe, v0
	v_cvt_u32_f32_e32 v0, v0
	s_nop 0
	v_readfirstlane_b32 s31, v0
	s_mul_i32 s30, s30, s31
	s_mul_hi_u32 s30, s31, s30
	s_add_i32 s31, s31, s30
	s_mul_hi_u32 s30, s11, s31
	s_mul_i32 s31, s30, s26
	s_sub_i32 s11, s11, s31
	s_add_i32 s34, s30, 1
	s_sub_i32 s31, s11, s26
	s_cmp_ge_u32 s11, s26
	s_cselect_b32 s30, s34, s30
	s_cselect_b32 s11, s31, s11
	s_add_i32 s31, s30, 1
	s_cmp_ge_u32 s11, s26
	s_cselect_b32 s11, s31, s30
	s_xor_b32 s11, s11, s29
	s_sub_i32 s26, s11, s29
	s_mul_i32 s11, s26, s28
	s_sub_i32 s10, s10, s11
	s_add_i32 s28, s27, s10

; __device__ __forceinline__ u32x4 pack8(const f32x4& a, const f32x4& b) { u32x4 w; w.x = pk2(a[0], a[1]); w.y = pk2(a[2], a[3]); w.z = pk2(b[0], b[1]); w.w = pk2(b[2], b[3]); return w; }
; __device__ __forceinline__ float sigm(float x) { return __builtin_amdgcn_rcpf(1.0f + __builtin_amdgcn_exp2f(x * -1.4426950408889634f)); }
; __device__ __forceinline__ float row_rstd(const float* ssp, int row, int fq) {
;     const f32x4 t = *((const f32x4*)(ssp + (size_t)row * 16) + fq); float s = (t[0] + t[1]) + (t[2] + t[3]); s += __shfl_xor(s, 16); s += __shfl_xor(s, 32); return rsqrtf(s * (1.0f / DM) + EPS); }
;     __device__ __forceinline__ void operator()(const f32x4 (&acc)[2][2][4][2], const Unit& u, int wr, int wc, int fr, int fq) const {
;         const int row0 = u.pm * BM + wr * 64 + fr, col0 = u.pn * 128 + 32 * wc + 8 * fq, lrow0 = row0 & (SEQ - 1);
;         bf16_t* const H = (bf16_t*)(ws + WS_SLAB + (size_t)(u.pm >> 4) * SLAB + SL_H);
;         float rx[2][4];
; #pragma unroll
;         for (int ai = 0; ai < 2; ++ai)
; #pragma unroll
;             for (int m = 0; m < 4; ++m) rx[ai][m] = row_rstd(ssp, row0 + ai * HALF + m * 16, fq);
; #pragma unroll
;         for (int ai = 0; ai < 2; ++ai)
; #pragma unroll
;             for (int m = 0; m < 4; ++m) { f32x4 o[2];
; #pragma unroll
;                 for (int n = 0; n < 2; ++n) { const f32x4 a = acc[ai][0][m][n] * rx[ai][m], b = acc[ai][1][m][n] * rx[ai][m];
; #pragma unroll
;                     for (int e = 0; e < 4; ++e) o[n][e] = a[e] * sigm(a[e]) * b[e]; }
;                 *(u32x4*)(H + (size_t)(lrow0 + ai * HALF + m * 16) * DFF + col0) = pack8(o[0], o[1]); asm volatile("" ::: "memory"); }
.LBB0_580:
	v_and_b32_e32 v129, 64, v229
	v_xor_b32_e32 v128, 16, v229
	v_add_u32_e32 v129, 64, v129
	v_cmp_lt_i32_e32 vcc, v128, v129
	v_lshl_add_u32 v130, s42, 8, v147
	v_ashrrev_i32_e32 v131, 31, v130
	v_cndmask_b32_e32 v128, v229, v128, vcc
	v_lshlrev_b32_e32 v162, 2, v128
	v_xor_b32_e32 v128, 32, v229
	v_cmp_lt_i32_e32 vcc, v128, v129
	s_mov_b32 s4, 0x358637bd
	s_ashr_i32 s29, s42, 4
	v_cndmask_b32_e32 v128, v229, v128, vcc
	v_lshlrev_b32_e32 v157, 2, v128
	v_lshlrev_b64 v[128:129], 6, v[130:131]
	v_lshl_add_u64 v[128:129], v[140:141], 0, v[128:129]
	global_load_dwordx4 v[170:173], v[128:129], off
	global_load_dwordx4 v[174:177], v[128:129], off offset:1024
	global_load_dwordx4 v[178:181], v[128:129], off offset:2048
	global_load_dwordx4 v[182:185], v[128:129], off offset:3072
	v_add_co_u32_e32 v206, vcc, s82, v128
	s_nop 1
	v_addc_co_u32_e32 v207, vcc, 0, v129, vcc
	global_load_dwordx4 v[186:189], v[206:207], off
	global_load_dwordx4 v[194:197], v[206:207], off offset:1024
	global_load_dwordx4 v[198:201], v[206:207], off offset:2048
	global_load_dwordx4 v[202:205], v[206:207], off offset:3072
	v_and_b32_e32 v155, 0xfcf, v130
	s_mul_hi_i32 s27, s29, 0x1c00000
	s_mul_i32 s29, s29, 0x1c00000
	s_add_u32 s10, s56, s29
	s_addc_u32 s11, s57, s27
	s_waitcnt vmcnt(7)
	v_mov_b32_e32 v164, v171
	v_mov_b32_e32 v165, v172
	v_mov_b32_e32 v171, v173
	v_pk_add_f32 v[164:165], v[164:165], v[170:171]
	s_waitcnt vmcnt(6)
	v_mov_b32_e32 v166, v175
	v_mov_b32_e32 v167, v176
	v_mov_b32_e32 v175, v177
	v_pk_add_f32 v[158:159], v[166:167], v[174:175]
	v_mov_b32_e32 v161, v164
	v_mov_b32_e32 v160, v158
	v_mov_b32_e32 v164, v159
	v_pk_add_f32 v[158:159], v[160:161], v[164:165]
	ds_bpermute_b32 v161, v162, v159
	ds_bpermute_b32 v160, v162, v158
	s_waitcnt lgkmcnt(0)
	v_pk_add_f32 v[158:159], v[158:159], v[160:161]
	ds_bpermute_b32 v161, v157, v159
	ds_bpermute_b32 v160, v157, v158
	s_waitcnt lgkmcnt(0)
	v_pk_add_f32 v[160:161], v[158:159], v[160:161]
	v_mov_b64_e32 v[158:159], s[4:5]
	v_pk_fma_f32 v[160:161], v[160:161], s[38:39], v[158:159] op_sel_hi:[1,0,0]
	s_nop 0
	v_mul_f32_e32 v131, 0x4b800000, v161
	v_cmp_gt_f32_e64 s[42:43], s99, v161
	v_cmp_gt_f32_e32 vcc, s99, v160
	s_nop 0
	v_cndmask_b32_e64 v131, v161, v131, s[42:43]
	v_rsq_f32_e32 v131, v131
	s_nop 0
	v_mul_f32_e32 v146, 0x45800000, v131
	v_cndmask_b32_e64 v156, v131, v146, s[42:43]
	v_mul_f32_e32 v131, 0x4b800000, v160
	v_cndmask_b32_e32 v131, v160, v131, vcc
	v_rsq_f32_e32 v131, v131
	v_pk_mul_f32 v[124:125], v[124:125], v[156:157] op_sel_hi:[1,0]
	v_pk_mul_f32 v[120:121], v[120:121], v[156:157] op_sel_hi:[1,0]
	v_mul_f32_e32 v146, 0x45800000, v131
	v_cndmask_b32_e32 v154, v131, v146, vcc
	v_pk_mul_f32 v[122:123], v[122:123], v[156:157] op_sel_hi:[1,0]
	v_pk_mul_f32 v[116:117], v[116:117], v[156:157] op_sel_hi:[1,0]
	v_pk_mul_f32 v[112:113], v[112:113], v[156:157] op_sel_hi:[1,0]
	v_pk_mul_f32 v[114:115], v[114:115], v[156:157] op_sel_hi:[1,0]
	v_pk_mul_f32 v[108:109], v[108:109], v[154:155] op_sel_hi:[1,0]
	v_pk_mul_f32 v[104:105], v[104:105], v[154:155] op_sel_hi:[1,0]
	v_pk_mul_f32 v[106:107], v[106:107], v[154:155] op_sel_hi:[1,0]
	v_pk_mul_f32 v[100:101], v[100:101], v[154:155] op_sel_hi:[1,0]
	v_pk_mul_f32 v[96:97], v[96:97], v[154:155] op_sel_hi:[1,0]
	v_pk_mul_f32 v[98:99], v[98:99], v[154:155] op_sel_hi:[1,0]
	s_waitcnt vmcnt(5)
	v_mov_b32_e32 v160, v179
	v_mov_b32_e32 v161, v180
	v_mov_b32_e32 v179, v181
	v_pk_add_f32 v[160:161], v[160:161], v[178:179]
	s_waitcnt vmcnt(4)
	v_mov_b32_e32 v130, v183
	v_mov_b32_e32 v131, v184
	v_mov_b32_e32 v183, v185
	v_pk_add_f32 v[130:131], v[130:131], v[182:183]
	v_mov_b32_e32 v165, v160
	v_mov_b32_e32 v164, v130
	v_mov_b32_e32 v160, v131
	v_pk_add_f32 v[130:131], v[164:165], v[160:161]
	ds_bpermute_b32 v161, v162, v131
	ds_bpermute_b32 v160, v162, v130
	s_waitcnt lgkmcnt(0)
	v_pk_add_f32 v[130:131], v[130:131], v[160:161]
	ds_bpermute_b32 v161, v157, v131
	ds_bpermute_b32 v160, v157, v130
	s_waitcnt lgkmcnt(0)
	v_pk_add_f32 v[130:131], v[130:131], v[160:161]
	s_nop 0
	v_pk_fma_f32 v[130:131], v[130:131], s[38:39], v[158:159] op_sel_hi:[1,0,0]
	s_nop 0
	v_mul_f32_e32 v146, 0x4b800000, v131
	v_cmp_gt_f32_e64 s[42:43], s99, v131
	v_cmp_gt_f32_e32 vcc, s99, v130
	s_nop 0
	v_cndmask_b32_e64 v131, v131, v146, s[42:43]
	v_rsq_f32_e32 v131, v131
	s_nop 0
	v_mul_f32_e32 v146, 0x45800000, v131
	v_cndmask_b32_e64 v152, v131, v146, s[42:43]
	v_mul_f32_e32 v131, 0x4b800000, v130
	v_cndmask_b32_e32 v130, v130, v131, vcc
	v_rsq_f32_e32 v130, v130
	v_pk_mul_f32 v[92:93], v[92:93], v[152:153] op_sel_hi:[1,0]
	v_pk_mul_f32 v[88:89], v[88:89], v[152:153] op_sel_hi:[1,0]
	v_pk_mul_f32 v[90:91], v[90:91], v[152:153] op_sel_hi:[1,0]
	v_mul_f32_e32 v131, 0x45800000, v130
	v_cndmask_b32_e32 v150, v130, v131, vcc
	v_pk_mul_f32 v[84:85], v[84:85], v[152:153] op_sel_hi:[1,0]
	v_pk_mul_f32 v[80:81], v[80:81], v[152:153] op_sel_hi:[1,0]
	v_pk_mul_f32 v[82:83], v[82:83], v[152:153] op_sel_hi:[1,0]
	v_pk_mul_f32 v[76:77], v[76:77], v[150:151] op_sel_hi:[1,0]
	v_pk_mul_f32 v[72:73], v[72:73], v[150:151] op_sel_hi:[1,0]
	v_pk_mul_f32 v[74:75], v[74:75], v[150:151] op_sel_hi:[1,0]
	v_pk_mul_f32 v[68:69], v[68:69], v[150:151] op_sel_hi:[1,0]
	v_pk_mul_f32 v[64:65], v[64:65], v[150:151] op_sel_hi:[1,0]
	v_pk_mul_f32 v[66:67], v[66:67], v[150:151] op_sel_hi:[1,0]
	s_waitcnt vmcnt(3)
	v_mov_b32_e32 v130, v187
	v_mov_b32_e32 v131, v188
	v_mov_b32_e32 v187, v189
	v_pk_add_f32 v[130:131], v[130:131], v[186:187]
	s_waitcnt vmcnt(2)
; __device__ __forceinline__ u32x4 pack8(const f32x4& a, const f32x4& b) { u32x4 w; w.x = pk2(a[0], a[1]); w.y = pk2(a[2], a[3]); w.z = pk2(b[0], b[1]); w.w = pk2(b[2], b[3]); return w; }
; __device__ __forceinline__ float sigm(float x) { return __builtin_amdgcn_rcpf(1.0f + __builtin_amdgcn_exp2f(x * -1.4426950408889634f)); }
;     __device__ __forceinline__ void operator()(const f32x4 (&acc)[2][2][4][2], const Unit& u, int wr, int wc, int fr, int fq) const {
;     ...
;             for (int m = 0; m < 4; ++m) rx[ai][m] = row_rstd(ssp, row0 + ai * HALF + m * 16, fq);
; #pragma unroll
;         for (int ai = 0; ai < 2; ++ai)
; #pragma unroll
;             for (int m = 0; m < 4; ++m) { f32x4 o[2];
; #pragma unroll
;                 for (int n = 0; n < 2; ++n) { const f32x4 a = acc[ai][0][m][n] * rx[ai][m], b = acc[ai][1][m][n] * rx[ai][m];
; #pragma unroll
;                     for (int e = 0; e < 4; ++e) o[n][e] = a[e] * sigm(a[e]) * b[e]; }
;                 *(u32x4*)(H + (size_t)(lrow0 + ai * HALF + m * 16) * DFF + col0) = pack8(o[0], o[1]); asm volatile("" ::: "memory"); }
	v_mov_b32_e32 v160, v195
	v_mov_b32_e32 v161, v196
	v_mov_b32_e32 v195, v197
	v_pk_add_f32 v[160:161], v[160:161], v[194:195]
	v_mov_b32_e32 v165, v130
	v_mov_b32_e32 v164, v160
	v_mov_b32_e32 v130, v161
	v_pk_add_f32 v[130:131], v[164:165], v[130:131]
	ds_bpermute_b32 v161, v162, v131
	ds_bpermute_b32 v160, v162, v130
	s_waitcnt lgkmcnt(0)
	v_pk_add_f32 v[130:131], v[130:131], v[160:161]
	ds_bpermute_b32 v161, v157, v131
	ds_bpermute_b32 v160, v157, v130
	s_waitcnt lgkmcnt(0)
	v_pk_add_f32 v[130:131], v[130:131], v[160:161]
	s_nop 0
	v_pk_fma_f32 v[130:131], v[130:131], s[38:39], v[158:159] op_sel_hi:[1,0,0]
	s_nop 0
	v_mul_f32_e32 v146, 0x4b800000, v131
	v_cmp_gt_f32_e64 s[42:43], s99, v131
	v_cmp_gt_f32_e32 vcc, s99, v130
	s_nop 0
	v_cndmask_b32_e64 v131, v131, v146, s[42:43]
	v_rsq_f32_e32 v131, v131
	s_nop 0
	v_mul_f32_e32 v146, 0x45800000, v131
	v_cndmask_b32_e64 v148, v131, v146, s[42:43]
	v_mul_f32_e32 v131, 0x4b800000, v130
	v_cndmask_b32_e32 v130, v130, v131, vcc
	v_rsq_f32_e32 v130, v130
	v_pk_mul_f32 v[60:61], v[60:61], v[148:149] op_sel_hi:[1,0]
	v_pk_mul_f32 v[56:57], v[56:57], v[148:149] op_sel_hi:[1,0]
	v_pk_mul_f32 v[58:59], v[58:59], v[148:149] op_sel_hi:[1,0]
	v_mul_f32_e32 v131, 0x45800000, v130
	v_cndmask_b32_e32 v146, v130, v131, vcc
	v_pk_mul_f32 v[52:53], v[52:53], v[148:149] op_sel_hi:[1,0]
	v_pk_mul_f32 v[48:49], v[48:49], v[148:149] op_sel_hi:[1,0]
	v_pk_mul_f32 v[50:51], v[50:51], v[148:149] op_sel_hi:[1,0]
	v_pk_mul_f32 v[44:45], v[44:45], v[146:147] op_sel_hi:[1,0]
	v_pk_mul_f32 v[40:41], v[40:41], v[146:147] op_sel_hi:[1,0]
	v_pk_mul_f32 v[42:43], v[42:43], v[146:147] op_sel_hi:[1,0]
	v_pk_mul_f32 v[36:37], v[36:37], v[146:147] op_sel_hi:[1,0]
	v_pk_mul_f32 v[32:33], v[32:33], v[146:147] op_sel_hi:[1,0]
	v_pk_mul_f32 v[34:35], v[34:35], v[146:147] op_sel_hi:[1,0]
	s_waitcnt vmcnt(1)
	v_mov_b32_e32 v130, v199
	v_mov_b32_e32 v131, v200
	v_mov_b32_e32 v199, v201
	v_pk_add_f32 v[160:161], v[130:131], v[198:199]
	s_waitcnt vmcnt(0)
	v_mov_b32_e32 v164, v203
	v_mov_b32_e32 v165, v204
	v_mov_b32_e32 v203, v205
	v_pk_add_f32 v[128:129], v[164:165], v[202:203]
	v_mov_b32_e32 v131, v160
	v_mov_b32_e32 v130, v128
	v_mov_b32_e32 v160, v129
	v_pk_add_f32 v[128:129], v[130:131], v[160:161]
	ds_bpermute_b32 v131, v162, v129
	ds_bpermute_b32 v130, v162, v128
	s_waitcnt lgkmcnt(0)
	v_pk_add_f32 v[128:129], v[128:129], v[130:131]
	ds_bpermute_b32 v131, v157, v129
	ds_bpermute_b32 v130, v157, v128
	s_waitcnt lgkmcnt(0)
	v_pk_add_f32 v[128:129], v[128:129], v[130:131]
	s_nop 0
	v_pk_fma_f32 v[128:129], v[128:129], s[38:39], v[158:159] op_sel_hi:[1,0,0]
	v_lshl_or_b32 v158, s59, 7, v151
	v_mul_f32_e32 v130, 0x4b800000, v129
	v_cmp_gt_f32_e64 s[42:43], s99, v129
	v_cmp_gt_f32_e32 vcc, s99, v128
	v_ashrrev_i32_e32 v159, 31, v158
	v_cndmask_b32_e64 v129, v129, v130, s[42:43]
	v_rsq_f32_e32 v129, v129
	v_lshl_add_u64 v[158:159], v[158:159], 1, s[10:11]
	v_mul_f32_e32 v130, 0x45800000, v129
	v_cndmask_b32_e64 v130, v129, v130, s[42:43]
	v_mul_f32_e32 v129, 0x4b800000, v128
	v_cndmask_b32_e32 v128, v128, v129, vcc
	v_rsq_f32_e32 v128, v128
	v_pk_mul_f32 v[28:29], v[28:29], v[130:131] op_sel_hi:[1,0]
	v_pk_mul_f32 v[24:25], v[24:25], v[130:131] op_sel_hi:[1,0]
	v_pk_mul_f32 v[26:27], v[26:27], v[130:131] op_sel_hi:[1,0]
	v_mul_f32_e32 v129, 0x45800000, v128
	v_cndmask_b32_e32 v128, v128, v129, vcc
	v_mul_f32_e32 v129, 0xbfb8aa3b, v124
	v_exp_f32_e32 v129, v129
	v_pk_mul_f32 v[20:21], v[20:21], v[130:131] op_sel_hi:[1,0]
	v_pk_mul_f32 v[16:17], v[16:17], v[130:131] op_sel_hi:[1,0]
	v_pk_mul_f32 v[18:19], v[18:19], v[130:131] op_sel_hi:[1,0]
	v_add_f32_e32 v129, 1.0, v129
	v_rcp_f32_e32 v160, v129
	v_mul_f32_e32 v129, 0xbfb8aa3b, v125
	v_exp_f32_e32 v129, v129
	s_mov_b64 s[42:43], -1
	v_add_f32_e32 v129, 1.0, v129
	v_rcp_f32_e32 v161, v129
	v_pk_mul_f32 v[12:13], v[12:13], v[128:129] op_sel_hi:[1,0]
	v_pk_mul_f32 v[8:9], v[8:9], v[128:129] op_sel_hi:[1,0]
	v_pk_mul_f32 v[10:11], v[10:11], v[128:129] op_sel_hi:[1,0]
	v_pk_mul_f32 v[124:125], v[124:125], v[160:161]
	v_pk_mul_f32 v[4:5], v[4:5], v[128:129] op_sel_hi:[1,0]
	v_pk_mul_f32 v[120:121], v[120:121], v[124:125]
	v_pk_mul_f32 v[124:125], v[126:127], v[156:157] op_sel_hi:[1,0]
	v_pk_mul_f32 v[0:1], v[0:1], v[128:129] op_sel_hi:[1,0]
	v_mul_f32_e32 v126, 0xbfb8aa3b, v124
	v_mul_f32_e32 v127, 0xbfb8aa3b, v125
	v_exp_f32_e32 v126, v126
	v_exp_f32_e32 v127, v127
	v_pk_mul_f32 v[2:3], v[2:3], v[128:129] op_sel_hi:[1,0]
	v_add_f32_e32 v126, 1.0, v126
	v_add_f32_e32 v127, 1.0, v127
	v_rcp_f32_e32 v126, v126
	v_rcp_f32_e32 v127, v127
	s_nop 0
	v_pk_mul_f32 v[124:125], v[124:125], v[126:127]
	s_nop 0
	v_pk_mul_f32 v[122:123], v[122:123], v[124:125]
	v_mul_f32_e32 v124, 0xbfb8aa3b, v116
	v_mul_f32_e32 v125, 0xbfb8aa3b, v117
	v_exp_f32_e32 v124, v124
	v_exp_f32_e32 v125, v125
	v_add_f32_e32 v124, 1.0, v124
	v_add_f32_e32 v125, 1.0, v125
	v_rcp_f32_e32 v124, v124
	v_rcp_f32_e32 v125, v125
	s_nop 0
	v_pk_mul_f32 v[116:117], v[116:117], v[124:125]
	s_nop 0
	v_pk_mul_f32 v[112:113], v[112:113], v[116:117]
	v_pk_mul_f32 v[116:117], v[118:119], v[156:157] op_sel_hi:[1,0]
	s_nop 0
	v_mul_f32_e32 v118, 0xbfb8aa3b, v116
	v_mul_f32_e32 v119, 0xbfb8aa3b, v117
	v_exp_f32_e32 v118, v118
	v_exp_f32_e32 v119, v119
	v_add_f32_e32 v118, 1.0, v118
	v_add_f32_e32 v119, 1.0, v119
	v_rcp_f32_e32 v118, v118
	v_rcp_f32_e32 v119, v119
	s_nop 0
	v_pk_mul_f32 v[116:117], v[116:117], v[118:119]
	s_nop 0
	v_pk_mul_f32 v[118:119], v[114:115], v[116:117]
	v_cvt_pk_bf16_f32 v116, v112, v113
	v_mul_u32_u24_e32 v112, 0xb00, v155
	v_lshlrev_b32_e32 v192, 1, v112
	v_cvt_pk_bf16_f32 v114, v120, v121
	v_cvt_pk_bf16_f32 v115, v122, v123
; __device__ __forceinline__ u32x4 pack8(const f32x4& a, const f32x4& b) { u32x4 w; w.x = pk2(a[0], a[1]); w.y = pk2(a[2], a[3]); w.z = pk2(b[0], b[1]); w.w = pk2(b[2], b[3]); return w; }
; __device__ __forceinline__ float sigm(float x) { return __builtin_amdgcn_rcpf(1.0f + __builtin_amdgcn_exp2f(x * -1.4426950408889634f)); }
;     __device__ __forceinline__ void operator()(const f32x4 (&acc)[2][2][4][2], const Unit& u, int wr, int wc, int fr, int fq) const {
;     ...
;         for (int ai = 0; ai < 2; ++ai)
; #pragma unroll
;             for (int m = 0; m < 4; ++m) { f32x4 o[2];
; #pragma unroll
;                 for (int n = 0; n < 2; ++n) { const f32x4 a = acc[ai][0][m][n] * rx[ai][m], b = acc[ai][1][m][n] * rx[ai][m];
; #pragma unroll
;                     for (int e = 0; e < 4; ++e) o[n][e] = a[e] * sigm(a[e]) * b[e]; }
;                 *(u32x4*)(H + (size_t)(lrow0 + ai * HALF + m * 16) * DFF + col0) = pack8(o[0], o[1]); asm volatile("" ::: "memory"); }
	v_cvt_pk_bf16_f32 v117, v118, v119
	v_lshl_add_u64 v[112:113], v[158:159], 0, v[192:193]
	global_store_dwordx4 v[112:113], v[114:117], off
	s_nop 1
	v_mul_f32_e32 v114, 0xbfb8aa3b, v108
	v_mul_f32_e32 v115, 0xbfb8aa3b, v109
	v_exp_f32_e32 v114, v114
	v_exp_f32_e32 v115, v115
	v_add_f32_e32 v114, 1.0, v114
	v_add_f32_e32 v115, 1.0, v115
	v_rcp_f32_e32 v114, v114
	v_rcp_f32_e32 v115, v115
	s_nop 0
	v_pk_mul_f32 v[108:109], v[108:109], v[114:115]
	s_nop 0
	v_pk_mul_f32 v[104:105], v[104:105], v[108:109]
	v_pk_mul_f32 v[108:109], v[110:111], v[154:155] op_sel_hi:[1,0]
	s_nop 0
	v_mul_f32_e32 v110, 0xbfb8aa3b, v108
	v_mul_f32_e32 v111, 0xbfb8aa3b, v109
	v_exp_f32_e32 v110, v110
	v_exp_f32_e32 v111, v111
	v_add_f32_e32 v110, 1.0, v110
	v_add_f32_e32 v111, 1.0, v111
	v_rcp_f32_e32 v110, v110
	v_rcp_f32_e32 v111, v111
	s_nop 0
	v_pk_mul_f32 v[108:109], v[108:109], v[110:111]
	s_nop 0
	v_pk_mul_f32 v[106:107], v[106:107], v[108:109]
	v_mul_f32_e32 v108, 0xbfb8aa3b, v100
	v_mul_f32_e32 v109, 0xbfb8aa3b, v101
	v_exp_f32_e32 v108, v108
	v_exp_f32_e32 v109, v109
	v_add_f32_e32 v108, 1.0, v108
	v_add_f32_e32 v109, 1.0, v109
	v_rcp_f32_e32 v108, v108
	v_rcp_f32_e32 v109, v109
	s_nop 0
	v_pk_mul_f32 v[100:101], v[100:101], v[108:109]
	s_nop 0
	v_pk_mul_f32 v[100:101], v[96:97], v[100:101]
	v_pk_mul_f32 v[96:97], v[102:103], v[154:155] op_sel_hi:[1,0]
	s_nop 0
	v_mul_f32_e32 v102, 0xbfb8aa3b, v96
	v_mul_f32_e32 v103, 0xbfb8aa3b, v97
	v_exp_f32_e32 v102, v102
	v_exp_f32_e32 v103, v103
	v_add_f32_e32 v102, 1.0, v102
	v_add_f32_e32 v103, 1.0, v103
	v_rcp_f32_e32 v102, v102
	v_rcp_f32_e32 v103, v103
	s_nop 0
	v_pk_mul_f32 v[96:97], v[96:97], v[102:103]
	s_nop 0
	v_pk_mul_f32 v[102:103], v[98:99], v[96:97]
	v_cvt_pk_bf16_f32 v98, v100, v101
	v_add_co_u32_e32 v100, vcc, s69, v112
	v_cvt_pk_bf16_f32 v96, v104, v105
	v_cvt_pk_bf16_f32 v97, v106, v107
	v_cvt_pk_bf16_f32 v99, v102, v103
	v_addc_co_u32_e32 v101, vcc, 0, v113, vcc
	global_store_dwordx4 v[100:101], v[96:99], off
	s_nop 1
	v_mul_f32_e32 v96, 0xbfb8aa3b, v92
	v_mul_f32_e32 v97, 0xbfb8aa3b, v93
	v_exp_f32_e32 v96, v96
	v_exp_f32_e32 v97, v97
	v_add_f32_e32 v96, 1.0, v96
	v_add_f32_e32 v97, 1.0, v97
	v_rcp_f32_e32 v96, v96
	v_rcp_f32_e32 v97, v97
	s_nop 0
	v_pk_mul_f32 v[92:93], v[92:93], v[96:97]
	s_nop 0
	v_pk_mul_f32 v[88:89], v[88:89], v[92:93]
	v_pk_mul_f32 v[92:93], v[94:95], v[152:153] op_sel_hi:[1,0]
	s_nop 0
	v_mul_f32_e32 v94, 0xbfb8aa3b, v92
	v_mul_f32_e32 v95, 0xbfb8aa3b, v93
	v_exp_f32_e32 v94, v94
	v_exp_f32_e32 v95, v95
	v_add_f32_e32 v94, 1.0, v94
	v_add_f32_e32 v95, 1.0, v95
	v_rcp_f32_e32 v94, v94
	v_rcp_f32_e32 v95, v95
	s_nop 0
	v_pk_mul_f32 v[92:93], v[92:93], v[94:95]
	s_nop 0
	v_pk_mul_f32 v[90:91], v[90:91], v[92:93]
	v_mul_f32_e32 v92, 0xbfb8aa3b, v84
	v_mul_f32_e32 v93, 0xbfb8aa3b, v85
	v_exp_f32_e32 v92, v92
	v_exp_f32_e32 v93, v93
	v_add_f32_e32 v92, 1.0, v92
	v_add_f32_e32 v93, 1.0, v93
	v_rcp_f32_e32 v92, v92
	v_rcp_f32_e32 v93, v93
	s_nop 0
	v_pk_mul_f32 v[84:85], v[84:85], v[92:93]
	s_nop 0
	v_pk_mul_f32 v[84:85], v[80:81], v[84:85]
	v_pk_mul_f32 v[80:81], v[86:87], v[152:153] op_sel_hi:[1,0]
	s_nop 0
	v_mul_f32_e32 v86, 0xbfb8aa3b, v80
	v_mul_f32_e32 v87, 0xbfb8aa3b, v81
	v_exp_f32_e32 v86, v86
	v_exp_f32_e32 v87, v87
	v_add_f32_e32 v86, 1.0, v86
	v_add_f32_e32 v87, 1.0, v87
	v_rcp_f32_e32 v86, v86
	v_rcp_f32_e32 v87, v87
	s_nop 0
	v_pk_mul_f32 v[80:81], v[80:81], v[86:87]
	s_nop 0
	v_pk_mul_f32 v[86:87], v[82:83], v[80:81]
	v_cvt_pk_bf16_f32 v82, v84, v85
	v_add_co_u32_e32 v84, vcc, s73, v112
	v_cvt_pk_bf16_f32 v80, v88, v89
	v_cvt_pk_bf16_f32 v81, v90, v91
	v_cvt_pk_bf16_f32 v83, v86, v87
	v_addc_co_u32_e32 v85, vcc, 0, v113, vcc
	global_store_dwordx4 v[84:85], v[80:83], off
	s_nop 1
	v_mul_f32_e32 v80, 0xbfb8aa3b, v76
	v_mul_f32_e32 v81, 0xbfb8aa3b, v77
	v_exp_f32_e32 v80, v80
	v_exp_f32_e32 v81, v81
	v_add_f32_e32 v80, 1.0, v80
	v_add_f32_e32 v81, 1.0, v81
	v_rcp_f32_e32 v80, v80
	v_rcp_f32_e32 v81, v81
	s_nop 0
	v_pk_mul_f32 v[76:77], v[76:77], v[80:81]
	s_nop 0
	v_pk_mul_f32 v[72:73], v[72:73], v[76:77]
	v_pk_mul_f32 v[76:77], v[78:79], v[150:151] op_sel_hi:[1,0]
	s_nop 0
	v_mul_f32_e32 v78, 0xbfb8aa3b, v76
	v_mul_f32_e32 v79, 0xbfb8aa3b, v77
	v_exp_f32_e32 v78, v78
	v_exp_f32_e32 v79, v79
	v_add_f32_e32 v78, 1.0, v78
	v_add_f32_e32 v79, 1.0, v79
	v_rcp_f32_e32 v78, v78
	v_rcp_f32_e32 v79, v79
	s_nop 0
	v_pk_mul_f32 v[76:77], v[76:77], v[78:79]
	s_nop 0
	v_pk_mul_f32 v[74:75], v[74:75], v[76:77]
	v_mul_f32_e32 v76, 0xbfb8aa3b, v68
	v_mul_f32_e32 v77, 0xbfb8aa3b, v69
	v_exp_f32_e32 v76, v76
	v_exp_f32_e32 v77, v77
	v_add_f32_e32 v76, 1.0, v76
	v_add_f32_e32 v77, 1.0, v77
	v_rcp_f32_e32 v76, v76
	v_rcp_f32_e32 v77, v77
	s_nop 0
	v_pk_mul_f32 v[68:69], v[68:69], v[76:77]
	s_nop 0
	v_pk_mul_f32 v[68:69], v[64:65], v[68:69]
	v_pk_mul_f32 v[64:65], v[70:71], v[150:151] op_sel_hi:[1,0]
	s_nop 0
	v_mul_f32_e32 v70, 0xbfb8aa3b, v64
	v_mul_f32_e32 v71, 0xbfb8aa3b, v65
	v_exp_f32_e32 v70, v70
	v_exp_f32_e32 v71, v71
	v_add_f32_e32 v70, 1.0, v70
	v_add_f32_e32 v71, 1.0, v71
	v_rcp_f32_e32 v70, v70
	v_rcp_f32_e32 v71, v71
	s_nop 0
	v_pk_mul_f32 v[64:65], v[64:65], v[70:71]
	s_nop 0
	v_pk_mul_f32 v[70:71], v[66:67], v[64:65]
	v_cvt_pk_bf16_f32 v66, v68, v69
	v_add_co_u32_e32 v68, vcc, s74, v112
	v_cvt_pk_bf16_f32 v64, v72, v73
	v_cvt_pk_bf16_f32 v65, v74, v75
	v_cvt_pk_bf16_f32 v67, v70, v71
	v_addc_co_u32_e32 v69, vcc, 0, v113, vcc
	global_store_dwordx4 v[68:69], v[64:67], off
	s_nop 1
	v_mul_f32_e32 v64, 0xbfb8aa3b, v60
	v_mul_f32_e32 v65, 0xbfb8aa3b, v61
	v_exp_f32_e32 v64, v64
	v_exp_f32_e32 v65, v65
	v_add_f32_e32 v64, 1.0, v64
	v_add_f32_e32 v65, 1.0, v65
	v_rcp_f32_e32 v64, v64
; #define PG8_BAR __builtin_amdgcn_s_barrier()
; __device__ __forceinline__ u32x4 pack8(const f32x4& a, const f32x4& b) { u32x4 w; w.x = pk2(a[0], a[1]); w.y = pk2(a[2], a[3]); w.z = pk2(b[0], b[1]); w.w = pk2(b[2], b[3]); return w; }
; __device__ __forceinline__ float sigm(float x) { return __builtin_amdgcn_rcpf(1.0f + __builtin_amdgcn_exp2f(x * -1.4426950408889634f)); }
; template <class Epi, class Sched, bool ALIGN_EPI = false, bool SP2 = false>
; __device__ __forceinline__ void gemm_phase(PG8_LAS unsigned char* lds, const Gemm g, const Sched& S, const Epi& E) {
;     ...
;         if constexpr (ALIGN_EPI) { if (wr == 1) PG8_BAR; }
;     }
;     __device__ __forceinline__ void operator()(const f32x4 (&acc)[2][2][4][2], const Unit& u, int wr, int wc, int fr, int fq) const {
;     ...
;         for (int ai = 0; ai < 2; ++ai)
; #pragma unroll
;             for (int m = 0; m < 4; ++m) { f32x4 o[2];
; #pragma unroll
;                 for (int n = 0; n < 2; ++n) { const f32x4 a = acc[ai][0][m][n] * rx[ai][m], b = acc[ai][1][m][n] * rx[ai][m];
; #pragma unroll
;                     for (int e = 0; e < 4; ++e) o[n][e] = a[e] * sigm(a[e]) * b[e]; }
;                 *(u32x4*)(H + (size_t)(lrow0 + ai * HALF + m * 16) * DFF + col0) = pack8(o[0], o[1]); asm volatile("" ::: "memory"); }
	v_rcp_f32_e32 v65, v65
	s_nop 0
	v_pk_mul_f32 v[60:61], v[60:61], v[64:65]
	s_nop 0
	v_pk_mul_f32 v[56:57], v[56:57], v[60:61]
	v_pk_mul_f32 v[60:61], v[62:63], v[148:149] op_sel_hi:[1,0]
	s_nop 0
	v_mul_f32_e32 v62, 0xbfb8aa3b, v60
	v_mul_f32_e32 v63, 0xbfb8aa3b, v61
	v_exp_f32_e32 v62, v62
	v_exp_f32_e32 v63, v63
	v_add_f32_e32 v62, 1.0, v62
	v_add_f32_e32 v63, 1.0, v63
	v_rcp_f32_e32 v62, v62
	v_rcp_f32_e32 v63, v63
	s_nop 0
	v_pk_mul_f32 v[60:61], v[60:61], v[62:63]
	s_nop 0
	v_pk_mul_f32 v[58:59], v[58:59], v[60:61]
	v_mul_f32_e32 v60, 0xbfb8aa3b, v52
	v_mul_f32_e32 v61, 0xbfb8aa3b, v53
	v_exp_f32_e32 v60, v60
	v_exp_f32_e32 v61, v61
	v_add_f32_e32 v60, 1.0, v60
	v_add_f32_e32 v61, 1.0, v61
	v_rcp_f32_e32 v60, v60
	v_rcp_f32_e32 v61, v61
	s_nop 0
	v_pk_mul_f32 v[52:53], v[52:53], v[60:61]
	s_nop 0
	v_pk_mul_f32 v[52:53], v[48:49], v[52:53]
	v_pk_mul_f32 v[48:49], v[54:55], v[148:149] op_sel_hi:[1,0]
	s_nop 0
	v_mul_f32_e32 v54, 0xbfb8aa3b, v48
	v_mul_f32_e32 v55, 0xbfb8aa3b, v49
	v_exp_f32_e32 v54, v54
	v_exp_f32_e32 v55, v55
	v_add_f32_e32 v54, 1.0, v54
	v_add_f32_e32 v55, 1.0, v55
	v_rcp_f32_e32 v54, v54
	v_rcp_f32_e32 v55, v55
	s_nop 0
	v_pk_mul_f32 v[48:49], v[48:49], v[54:55]
	s_nop 0
	v_pk_mul_f32 v[54:55], v[50:51], v[48:49]
	v_cvt_pk_bf16_f32 v50, v52, v53
	v_add_co_u32_e32 v52, vcc, s75, v112
	v_cvt_pk_bf16_f32 v48, v56, v57
	v_cvt_pk_bf16_f32 v49, v58, v59
	v_cvt_pk_bf16_f32 v51, v54, v55
	v_addc_co_u32_e32 v53, vcc, 0, v113, vcc
	global_store_dwordx4 v[52:53], v[48:51], off
	s_nop 1
	v_mul_f32_e32 v48, 0xbfb8aa3b, v44
	v_mul_f32_e32 v49, 0xbfb8aa3b, v45
	v_exp_f32_e32 v48, v48
	v_exp_f32_e32 v49, v49
	v_add_f32_e32 v48, 1.0, v48
	v_add_f32_e32 v49, 1.0, v49
	v_rcp_f32_e32 v48, v48
	v_rcp_f32_e32 v49, v49
	s_nop 0
	v_pk_mul_f32 v[44:45], v[44:45], v[48:49]
	s_nop 0
	v_pk_mul_f32 v[40:41], v[40:41], v[44:45]
	v_pk_mul_f32 v[44:45], v[46:47], v[146:147] op_sel_hi:[1,0]
	s_nop 0
	v_mul_f32_e32 v46, 0xbfb8aa3b, v44
	v_mul_f32_e32 v47, 0xbfb8aa3b, v45
	v_exp_f32_e32 v46, v46
	v_exp_f32_e32 v47, v47
	v_add_f32_e32 v46, 1.0, v46
	v_add_f32_e32 v47, 1.0, v47
	v_rcp_f32_e32 v46, v46
	v_rcp_f32_e32 v47, v47
	s_nop 0
	v_pk_mul_f32 v[44:45], v[44:45], v[46:47]
	s_nop 0
	v_pk_mul_f32 v[42:43], v[42:43], v[44:45]
	v_mul_f32_e32 v44, 0xbfb8aa3b, v36
	v_mul_f32_e32 v45, 0xbfb8aa3b, v37
	v_exp_f32_e32 v44, v44
	v_exp_f32_e32 v45, v45
	v_add_f32_e32 v44, 1.0, v44
	v_add_f32_e32 v45, 1.0, v45
	v_rcp_f32_e32 v44, v44
	v_rcp_f32_e32 v45, v45
	s_nop 0
	v_pk_mul_f32 v[36:37], v[36:37], v[44:45]
	s_nop 0
	v_pk_mul_f32 v[36:37], v[32:33], v[36:37]
	v_pk_mul_f32 v[32:33], v[38:39], v[146:147] op_sel_hi:[1,0]
	s_nop 0
	v_mul_f32_e32 v38, 0xbfb8aa3b, v32
	v_mul_f32_e32 v39, 0xbfb8aa3b, v33
	v_exp_f32_e32 v38, v38
	v_exp_f32_e32 v39, v39
	v_add_f32_e32 v38, 1.0, v38
	v_add_f32_e32 v39, 1.0, v39
	v_rcp_f32_e32 v38, v38
	v_rcp_f32_e32 v39, v39
	s_nop 0
	v_pk_mul_f32 v[32:33], v[32:33], v[38:39]
	s_nop 0
	v_pk_mul_f32 v[38:39], v[34:35], v[32:33]
	v_cvt_pk_bf16_f32 v34, v36, v37
	v_add_co_u32_e32 v36, vcc, s76, v112
	v_cvt_pk_bf16_f32 v32, v40, v41
	v_cvt_pk_bf16_f32 v33, v42, v43
	v_cvt_pk_bf16_f32 v35, v38, v39
	v_addc_co_u32_e32 v37, vcc, 0, v113, vcc
	global_store_dwordx4 v[36:37], v[32:35], off
	s_nop 1
	v_mul_f32_e32 v32, 0xbfb8aa3b, v28
	v_mul_f32_e32 v33, 0xbfb8aa3b, v29
	v_exp_f32_e32 v32, v32
	v_exp_f32_e32 v33, v33
	v_add_f32_e32 v32, 1.0, v32
	v_add_f32_e32 v33, 1.0, v33
	v_rcp_f32_e32 v32, v32
	v_rcp_f32_e32 v33, v33
	s_nop 0
	v_pk_mul_f32 v[28:29], v[28:29], v[32:33]
	s_nop 0
	v_pk_mul_f32 v[24:25], v[24:25], v[28:29]
	v_pk_mul_f32 v[28:29], v[30:31], v[130:131] op_sel_hi:[1,0]
	s_nop 0
	v_mul_f32_e32 v30, 0xbfb8aa3b, v28
	v_mul_f32_e32 v31, 0xbfb8aa3b, v29
	v_exp_f32_e32 v30, v30
	v_exp_f32_e32 v31, v31
	v_add_f32_e32 v30, 1.0, v30
	v_add_f32_e32 v31, 1.0, v31
	v_rcp_f32_e32 v30, v30
	v_rcp_f32_e32 v31, v31
	s_nop 0
	v_pk_mul_f32 v[28:29], v[28:29], v[30:31]
	s_nop 0
	v_pk_mul_f32 v[26:27], v[26:27], v[28:29]
	v_mul_f32_e32 v28, 0xbfb8aa3b, v20
	v_mul_f32_e32 v29, 0xbfb8aa3b, v21
	v_exp_f32_e32 v28, v28
	v_exp_f32_e32 v29, v29
	v_add_f32_e32 v28, 1.0, v28
	v_add_f32_e32 v29, 1.0, v29
	v_rcp_f32_e32 v28, v28
	v_rcp_f32_e32 v29, v29
	s_nop 0
	v_pk_mul_f32 v[20:21], v[20:21], v[28:29]
	s_nop 0
	v_pk_mul_f32 v[20:21], v[16:17], v[20:21]
	v_pk_mul_f32 v[16:17], v[22:23], v[130:131] op_sel_hi:[1,0]
	s_nop 0
	v_mul_f32_e32 v22, 0xbfb8aa3b, v16
	v_mul_f32_e32 v23, 0xbfb8aa3b, v17
	v_exp_f32_e32 v22, v22
	v_exp_f32_e32 v23, v23
	v_add_f32_e32 v22, 1.0, v22
	v_add_f32_e32 v23, 1.0, v23
	v_rcp_f32_e32 v22, v22
	v_rcp_f32_e32 v23, v23
	s_nop 0
	v_pk_mul_f32 v[16:17], v[16:17], v[22:23]
	s_nop 0
	v_pk_mul_f32 v[22:23], v[18:19], v[16:17]
	v_cvt_pk_bf16_f32 v18, v20, v21
	v_add_co_u32_e32 v20, vcc, s77, v112
	v_cvt_pk_bf16_f32 v16, v24, v25
	v_cvt_pk_bf16_f32 v17, v26, v27
	v_cvt_pk_bf16_f32 v19, v22, v23
	v_addc_co_u32_e32 v21, vcc, 0, v113, vcc
	global_store_dwordx4 v[20:21], v[16:19], off
	s_nop 1
	v_mul_f32_e32 v16, 0xbfb8aa3b, v12
	v_mul_f32_e32 v17, 0xbfb8aa3b, v13
	v_exp_f32_e32 v16, v16
	v_exp_f32_e32 v17, v17
	v_add_f32_e32 v16, 1.0, v16
	v_add_f32_e32 v17, 1.0, v17
	v_rcp_f32_e32 v16, v16
	v_rcp_f32_e32 v17, v17
	s_nop 0
	v_pk_mul_f32 v[12:13], v[12:13], v[16:17]
	s_nop 0
	v_pk_mul_f32 v[8:9], v[8:9], v[12:13]
	v_pk_mul_f32 v[12:13], v[14:15], v[128:129] op_sel_hi:[1,0]
	s_nop 0
	v_mul_f32_e32 v14, 0xbfb8aa3b, v12
	v_mul_f32_e32 v15, 0xbfb8aa3b, v13
	v_exp_f32_e32 v14, v14
	v_exp_f32_e32 v15, v15
	v_add_f32_e32 v14, 1.0, v14
	v_add_f32_e32 v15, 1.0, v15
	v_rcp_f32_e32 v14, v14
	v_rcp_f32_e32 v15, v15
	s_nop 0
	v_pk_mul_f32 v[12:13], v[12:13], v[14:15]
	s_nop 0
	v_pk_mul_f32 v[10:11], v[10:11], v[12:13]
	v_mul_f32_e32 v12, 0xbfb8aa3b, v4
	v_mul_f32_e32 v13, 0xbfb8aa3b, v5
	v_exp_f32_e32 v12, v12
	v_exp_f32_e32 v13, v13
	v_add_f32_e32 v12, 1.0, v12
	v_add_f32_e32 v13, 1.0, v13
	v_rcp_f32_e32 v12, v12
	v_rcp_f32_e32 v13, v13
	s_nop 0
	v_pk_mul_f32 v[4:5], v[4:5], v[12:13]
	s_nop 0
	v_pk_mul_f32 v[4:5], v[0:1], v[4:5]
	v_pk_mul_f32 v[0:1], v[6:7], v[128:129] op_sel_hi:[1,0]
	s_nop 0
	v_mul_f32_e32 v6, 0xbfb8aa3b, v0
	v_mul_f32_e32 v7, 0xbfb8aa3b, v1
	v_exp_f32_e32 v6, v6
	v_exp_f32_e32 v7, v7
	v_add_f32_e32 v6, 1.0, v6
	v_add_f32_e32 v7, 1.0, v7
	v_rcp_f32_e32 v6, v6
	v_rcp_f32_e32 v7, v7
	s_nop 0
	v_pk_mul_f32 v[0:1], v[0:1], v[6:7]
	s_nop 0
	v_pk_mul_f32 v[6:7], v[2:3], v[0:1]
	v_cvt_pk_bf16_f32 v2, v4, v5
	v_add_co_u32_e32 v4, vcc, 0xf2000, v112
	v_cvt_pk_bf16_f32 v0, v8, v9
	v_cvt_pk_bf16_f32 v1, v10, v11
	v_cvt_pk_bf16_f32 v3, v6, v7
	v_addc_co_u32_e32 v5, vcc, 0, v113, vcc
	global_store_dwordx4 v[4:5], v[0:3], off
	s_andn2_b64 vcc, exec, s[40:41]
	s_cbranch_vccnz .LBB0_573
	s_branch .LBB0_572
